# top-13 selection: wave maximum through row_bcast DPP and an SGPR (no LDS swizzle / permlane), index conversion once after the 13 rounds
# speedup vs baseline: 1.0190x; 1.0026x over previous
; #define LAS __attribute__((address_space(3)))
; __device__ __forceinline__ bf16_t tobf(float x) { return (bf16_t)pk2(x, 0.f); }
; __device__ __forceinline__ void nsa_quad_pre(int bg, int quad, const bf16_t* Q, const bf16_t* KV, const bf16_t* KCMP, const bf16_t* VCMPT, const float* GN, bf16_t* ONSA, ...
;     ...
;     for (int tt = 0; tt < 4; ++tt) {
;         const int tok = t0 + tt, cur = tok >> 6;
;         if (cur < 16) { if (lane < 16) selq[tt * 16 + lane] = lane; }
;         else {
;             unsigned k0 = 0u, k1 = 0u;
;             { const int j = lane; if (j >= 1 && j <= cur - 2) { const LAS float* ps = psum + tt * 512 + 4 * j - 1; const float v = ps[0] + ps[1] + ps[2] + ps[3] + ps[4]; k0 = (__builtin_bit_cast(unsigned, v) & ~127u) | (unsigned)(127 - j); } }
;             { const int j = lane + 64; if (j <= cur - 2) { const LAS float* ps = psum + tt * 512 + 4 * j - 1; const float v = ps[0] + ps[1] + ps[2] + ps[3] + ps[4]; k1 = (__builtin_bit_cast(unsigned, v) & ~127u) | (unsigned)(127 - j); } }
;             for (int it = 0; it < 13; ++it) {
;                 unsigned m = k0 > k1 ? k0 : k1;
; #pragma unroll
;                 for (int off = 32; off >= 1; off >>= 1) { const unsigned o = (unsigned)__shfl_xor((int)m, off); m = o > m ? o : m; }
;     ...
;     for (int tt = 0; tt < 4; ++tt) { const float gc = GN[(size_t)(b * SEQ + t0 + tt) * 48 + (g * 4 + q4) * 3];
;         bf16_t* op = ONSA + (size_t)(b * SEQ + t0 + tt) * 1024 + (g * 4 + q4) * 64 + r16;
; #pragma unroll
;         for (int nt = 0; nt < 4; ++nt) op[nt * 16] = tobf(gc * oc[nt][tt]); }
.Lcmp_tail_q0p2:
	s_waitcnt vmcnt(2) lgkmcnt(0)
	s_barrier
	s_add_i32 s75, s75, 1
	s_cmp_eq_u32 s75, 3
	s_cselect_b32 s75, 0, s75
	s_add_i32 s57, s57, 1
	s_cmp_lt_i32 s57, s74
	s_cbranch_scc1 .Lcmp_top_q0p2
	s_waitcnt lgkmcnt(0)
	s_nop 7
	s_nop 3
	v_and_b32_e32 v232, 15, v184
	v_lshrrev_b32_e32 v233, 4, v184
	v_and_b32_e32 v234, 3, v232
	v_lshrrev_b32_e32 v235, 2, v232
	s_add_i32 s0, s47, s97
	v_add_u32_e32 v253, s0, v234
	s_and_b32 s1, s88, 3
	s_lshl_b32 s1, s1, 2
	v_add_u32_e32 v0, s1, v235
	v_lshlrev_b32_e32 v98, 7, v0
	v_lshl_add_u32 v98, v253, 11, v98
	v_lshl_add_u32 v98, v233, 3, v98
	v_mul_u32_u24_e32 v99, 0xc0, v253
	v_mul_u32_u24_e32 v0, 12, v0
	v_add_u32_e32 v99, v99, v0
	s_add_u32 s72, s30, 0x38310000
	s_addc_u32 s73, s31, 0
	s_add_u32 s14, s30, 0xf900000
	s_addc_u32 s15, s31, 0
	global_load_dword v232, v99, s[72:73]
	s_waitcnt vmcnt(0)
	v_mul_f32_e32 v2, v2, v232
	v_mul_f32_e32 v3, v3, v232
	v_mul_f32_e32 v4, v4, v232
	v_mul_f32_e32 v5, v5, v232
	v_mul_f32_e32 v6, v6, v232
	v_mul_f32_e32 v7, v7, v232
	v_mul_f32_e32 v8, v8, v232
	v_mul_f32_e32 v9, v9, v232
	v_mul_f32_e32 v10, v10, v232
	v_mul_f32_e32 v11, v11, v232
	v_mul_f32_e32 v12, v12, v232
	v_mul_f32_e32 v13, v13, v232
	v_mul_f32_e32 v14, v14, v232
	v_mul_f32_e32 v15, v15, v232
	v_mul_f32_e32 v16, v16, v232
	v_mul_f32_e32 v17, v17, v232
	v_cvt_pk_bf16_f32 v216, v2, v3
	v_cvt_pk_bf16_f32 v217, v4, v5
	v_cvt_pk_bf16_f32 v218, v6, v7
	v_cvt_pk_bf16_f32 v219, v8, v9
	v_cvt_pk_bf16_f32 v220, v10, v11
	v_cvt_pk_bf16_f32 v221, v12, v13
	v_cvt_pk_bf16_f32 v222, v14, v15
	v_cvt_pk_bf16_f32 v223, v16, v17
	global_store_dwordx2 v98, v[216:217], s[14:15] offset:0
	global_store_dwordx2 v98, v[218:219], s[14:15] offset:32
	global_store_dwordx2 v98, v[220:221], s[14:15] offset:64
	global_store_dwordx2 v98, v[222:223], s[14:15] offset:96
	s_waitcnt lgkmcnt(0)
	s_cmp_gt_i32 s18, 15
	s_cbranch_scc0 .Ltopk_small_q0
	s_lshl_b32 s19, s80, 10
	s_add_i32 s19, s19, 56384
	v_lshlrev_b32_e32 v96, 4, v184
	v_add_u32_e32 v96, s19, v96
	v_add_u32_e32 v97, 0xfffffffc, v96
	v_sub_u32_e32 v94, 127, v184
	v_sub_u32_e32 v95, 63, v184
	s_mov_b32 s54, 0xffffff80
	s_add_i32 s21, s18, -2
	v_add_u32_e32 v236, 64, v184
	ds_read_b32 v86, v97 offset:0
	ds_read_b128 v[50:53], v96 offset:0
	ds_read_b32 v87, v97 offset:1024
	ds_read_b128 v[54:57], v96 offset:1024
	ds_read_b32 v88, v97 offset:2048
	ds_read_b128 v[58:61], v96 offset:2048
	ds_read_b32 v89, v97 offset:3072
	ds_read_b128 v[62:65], v96 offset:3072
	s_waitcnt lgkmcnt(6)
	v_add_f32_e32 v86, v86, v50
	v_add_f32_e32 v86, v86, v51
	v_add_f32_e32 v86, v86, v52
	v_add_f32_e32 v86, v86, v53
	v_and_or_b32 v18, v86, s54, v94
	s_waitcnt lgkmcnt(4)
	v_add_f32_e32 v87, v87, v54
	v_add_f32_e32 v87, v87, v55
	v_add_f32_e32 v87, v87, v56
	v_add_f32_e32 v87, v87, v57
	v_and_or_b32 v22, v87, s54, v95
	s_waitcnt lgkmcnt(2)
	v_add_f32_e32 v88, v88, v58
	v_add_f32_e32 v88, v88, v59
	v_add_f32_e32 v88, v88, v60
	v_add_f32_e32 v88, v88, v61
	v_and_or_b32 v19, v88, s54, v94
	s_waitcnt lgkmcnt(0)
	v_add_f32_e32 v89, v89, v62
	v_add_f32_e32 v89, v89, v63
	v_add_f32_e32 v89, v89, v64
	v_add_f32_e32 v89, v89, v65
	v_and_or_b32 v23, v89, s54, v95
	ds_read_b32 v90, v97 offset:4096
	ds_read_b128 v[66:69], v96 offset:4096
	ds_read_b32 v91, v97 offset:5120
	ds_read_b128 v[70:73], v96 offset:5120
	ds_read_b32 v92, v97 offset:6144
	ds_read_b128 v[74:77], v96 offset:6144
	ds_read_b32 v93, v97 offset:7168
	ds_read_b128 v[78:81], v96 offset:7168
	s_waitcnt lgkmcnt(6)
	v_add_f32_e32 v90, v90, v66
	v_add_f32_e32 v90, v90, v67
	v_add_f32_e32 v90, v90, v68
	v_add_f32_e32 v90, v90, v69
	v_and_or_b32 v20, v90, s54, v94
	s_waitcnt lgkmcnt(4)
	v_add_f32_e32 v91, v91, v70
	v_add_f32_e32 v91, v91, v71
	v_add_f32_e32 v91, v91, v72
	v_add_f32_e32 v91, v91, v73
	v_and_or_b32 v24, v91, s54, v95
	s_waitcnt lgkmcnt(2)
	v_add_f32_e32 v92, v92, v74
	v_add_f32_e32 v92, v92, v75
	v_add_f32_e32 v92, v92, v76
	v_add_f32_e32 v92, v92, v77
	v_and_or_b32 v21, v92, s54, v94
	s_waitcnt lgkmcnt(0)
	v_add_f32_e32 v93, v93, v78
	v_add_f32_e32 v93, v93, v79
	v_add_f32_e32 v93, v93, v80
	v_add_f32_e32 v93, v93, v81
	v_and_or_b32 v25, v93, s54, v95
	v_cmp_le_i32_e64 s[14:15], v184, s21
	v_cmp_lt_i32_e64 s[34:35], 0, v184
	s_nop 0
	s_and_b64 s[14:15], s[14:15], s[34:35]
	v_cmp_le_i32_e64 s[34:35], v236, s21
	v_cndmask_b32_e64 v18, 0, v18, s[14:15]
	s_nop 0
	v_cndmask_b32_e64 v22, 0, v22, s[34:35]
	v_mov_b32_e32 v82, 127
	v_cndmask_b32_e64 v19, 0, v19, s[14:15]
	v_cndmask_b32_e64 v23, 0, v23, s[34:35]
	v_mov_b32_e32 v83, 127
	v_cndmask_b32_e64 v20, 0, v20, s[14:15]
	v_cndmask_b32_e64 v24, 0, v24, s[34:35]
	v_mov_b32_e32 v84, 127
	v_cndmask_b32_e64 v21, 0, v21, s[14:15]
	v_cndmask_b32_e64 v25, 0, v25, s[34:35]
	v_mov_b32_e32 v85, 127
	v_max_u32_e32 v26, v18, v22
	v_max_u32_e32 v27, v19, v23
	v_max_u32_e32 v28, v20, v24
	v_max_u32_e32 v29, v21, v25
	v_max_u32_dpp v26, v26, v26 quad_perm:[1,0,3,2] row_mask:0xf bank_mask:0xf
	v_max_u32_dpp v27, v27, v27 quad_perm:[1,0,3,2] row_mask:0xf bank_mask:0xf
	v_max_u32_dpp v28, v28, v28 quad_perm:[1,0,3,2] row_mask:0xf bank_mask:0xf
	v_max_u32_dpp v29, v29, v29 quad_perm:[1,0,3,2] row_mask:0xf bank_mask:0xf
	v_max_u32_dpp v26, v26, v26 quad_perm:[2,3,0,1] row_mask:0xf bank_mask:0xf
	v_max_u32_dpp v27, v27, v27 quad_perm:[2,3,0,1] row_mask:0xf bank_mask:0xf
	v_max_u32_dpp v28, v28, v28 quad_perm:[2,3,0,1] row_mask:0xf bank_mask:0xf
	v_max_u32_dpp v29, v29, v29 quad_perm:[2,3,0,1] row_mask:0xf bank_mask:0xf
	v_max_u32_dpp v26, v26, v26 row_half_mirror row_mask:0xf bank_mask:0xf
	v_max_u32_dpp v27, v27, v27 row_half_mirror row_mask:0xf bank_mask:0xf
	v_max_u32_dpp v28, v28, v28 row_half_mirror row_mask:0xf bank_mask:0xf
; __device__ __forceinline__ void nsa_quad_pre(int bg, int quad, const bf16_t* Q, const bf16_t* KV, const bf16_t* KCMP, const bf16_t* VCMPT, const float* GN, bf16_t* ONSA, ...
;     ...
;             for (int it = 0; it < 13; ++it) {
;                 unsigned m = k0 > k1 ? k0 : k1;
; #pragma unroll
;                 for (int off = 32; off >= 1; off >>= 1) { const unsigned o = (unsigned)__shfl_xor((int)m, off); m = o > m ? o : m; }
;                 if (k0 == m) k0 = 0u; if (k1 == m) k1 = 0u;
;                 if (lane == 0) selq[tt * 16 + it] = 127 - (int)(m & 127u);
	v_max_u32_dpp v29, v29, v29 row_half_mirror row_mask:0xf bank_mask:0xf
	v_max_u32_dpp v26, v26, v26 row_mirror row_mask:0xf bank_mask:0xf
	v_max_u32_dpp v27, v27, v27 row_mirror row_mask:0xf bank_mask:0xf
	v_max_u32_dpp v28, v28, v28 row_mirror row_mask:0xf bank_mask:0xf
	v_max_u32_dpp v29, v29, v29 row_mirror row_mask:0xf bank_mask:0xf
	v_max_u32_dpp v26, v26, v26 row_bcast:15 row_mask:0xa bank_mask:0xf
	v_max_u32_dpp v27, v27, v27 row_bcast:15 row_mask:0xa bank_mask:0xf
	v_max_u32_dpp v28, v28, v28 row_bcast:15 row_mask:0xa bank_mask:0xf
	v_max_u32_dpp v29, v29, v29 row_bcast:15 row_mask:0xa bank_mask:0xf
	v_max_u32_dpp v26, v26, v26 row_bcast:31 row_mask:0xc bank_mask:0xf
	v_max_u32_dpp v27, v27, v27 row_bcast:31 row_mask:0xc bank_mask:0xf
	v_max_u32_dpp v28, v28, v28 row_bcast:31 row_mask:0xc bank_mask:0xf
	v_max_u32_dpp v29, v29, v29 row_bcast:31 row_mask:0xc bank_mask:0xf
	v_readlane_b32 s14, v26, 63
	v_readlane_b32 s15, v27, 63
	v_readlane_b32 s34, v28, 63
	v_readlane_b32 s35, v29, 63
	v_writelane_b32 v82, s14, 0
	v_writelane_b32 v83, s15, 0
	v_writelane_b32 v84, s34, 0
	v_writelane_b32 v85, s35, 0
	v_cmp_ne_u32_e64 s[42:43], s14, v18
	v_cmp_ne_u32_e64 s[66:67], s14, v22
	v_cmp_ne_u32_e64 s[0:1], s15, v19
	v_cmp_ne_u32_e32 vcc, s15, v23
	v_cndmask_b32_e64 v18, 0, v18, s[42:43]
	v_cndmask_b32_e64 v22, 0, v22, s[66:67]
	v_cndmask_b32_e64 v19, 0, v19, s[0:1]
	v_cndmask_b32_e32 v23, 0, v23, vcc
	v_cmp_ne_u32_e64 s[42:43], s34, v20
	v_cmp_ne_u32_e64 s[66:67], s34, v24
	v_cmp_ne_u32_e64 s[0:1], s35, v21
	v_cmp_ne_u32_e32 vcc, s35, v25
	v_cndmask_b32_e64 v20, 0, v20, s[42:43]
	v_cndmask_b32_e64 v24, 0, v24, s[66:67]
	v_cndmask_b32_e64 v21, 0, v21, s[0:1]
	v_cndmask_b32_e32 v25, 0, v25, vcc
	v_max_u32_e32 v26, v18, v22
	v_max_u32_e32 v27, v19, v23
	v_max_u32_e32 v28, v20, v24
	v_max_u32_e32 v29, v21, v25
	v_max_u32_dpp v26, v26, v26 quad_perm:[1,0,3,2] row_mask:0xf bank_mask:0xf
	v_max_u32_dpp v27, v27, v27 quad_perm:[1,0,3,2] row_mask:0xf bank_mask:0xf
	v_max_u32_dpp v28, v28, v28 quad_perm:[1,0,3,2] row_mask:0xf bank_mask:0xf
	v_max_u32_dpp v29, v29, v29 quad_perm:[1,0,3,2] row_mask:0xf bank_mask:0xf
	v_max_u32_dpp v26, v26, v26 quad_perm:[2,3,0,1] row_mask:0xf bank_mask:0xf
	v_max_u32_dpp v27, v27, v27 quad_perm:[2,3,0,1] row_mask:0xf bank_mask:0xf
	v_max_u32_dpp v28, v28, v28 quad_perm:[2,3,0,1] row_mask:0xf bank_mask:0xf
	v_max_u32_dpp v29, v29, v29 quad_perm:[2,3,0,1] row_mask:0xf bank_mask:0xf
	v_max_u32_dpp v26, v26, v26 row_half_mirror row_mask:0xf bank_mask:0xf
	v_max_u32_dpp v27, v27, v27 row_half_mirror row_mask:0xf bank_mask:0xf
	v_max_u32_dpp v28, v28, v28 row_half_mirror row_mask:0xf bank_mask:0xf
	v_max_u32_dpp v29, v29, v29 row_half_mirror row_mask:0xf bank_mask:0xf
	v_max_u32_dpp v26, v26, v26 row_mirror row_mask:0xf bank_mask:0xf
	v_max_u32_dpp v27, v27, v27 row_mirror row_mask:0xf bank_mask:0xf
	v_max_u32_dpp v28, v28, v28 row_mirror row_mask:0xf bank_mask:0xf
	v_max_u32_dpp v29, v29, v29 row_mirror row_mask:0xf bank_mask:0xf
	v_max_u32_dpp v26, v26, v26 row_bcast:15 row_mask:0xa bank_mask:0xf
	v_max_u32_dpp v27, v27, v27 row_bcast:15 row_mask:0xa bank_mask:0xf
	v_max_u32_dpp v28, v28, v28 row_bcast:15 row_mask:0xa bank_mask:0xf
	v_max_u32_dpp v29, v29, v29 row_bcast:15 row_mask:0xa bank_mask:0xf
	v_max_u32_dpp v26, v26, v26 row_bcast:31 row_mask:0xc bank_mask:0xf
	v_max_u32_dpp v27, v27, v27 row_bcast:31 row_mask:0xc bank_mask:0xf
	v_max_u32_dpp v28, v28, v28 row_bcast:31 row_mask:0xc bank_mask:0xf
	v_max_u32_dpp v29, v29, v29 row_bcast:31 row_mask:0xc bank_mask:0xf
	v_readlane_b32 s14, v26, 63
	v_readlane_b32 s15, v27, 63
	v_readlane_b32 s34, v28, 63
	v_readlane_b32 s35, v29, 63
	v_writelane_b32 v82, s14, 1
	v_writelane_b32 v83, s15, 1
	v_writelane_b32 v84, s34, 1
	v_writelane_b32 v85, s35, 1
	v_cmp_ne_u32_e64 s[42:43], s14, v18
	v_cmp_ne_u32_e64 s[66:67], s14, v22
	v_cmp_ne_u32_e64 s[0:1], s15, v19
	v_cmp_ne_u32_e32 vcc, s15, v23
	v_cndmask_b32_e64 v18, 0, v18, s[42:43]
	v_cndmask_b32_e64 v22, 0, v22, s[66:67]
	v_cndmask_b32_e64 v19, 0, v19, s[0:1]
	v_cndmask_b32_e32 v23, 0, v23, vcc
	v_cmp_ne_u32_e64 s[42:43], s34, v20
	v_cmp_ne_u32_e64 s[66:67], s34, v24
	v_cmp_ne_u32_e64 s[0:1], s35, v21
	v_cmp_ne_u32_e32 vcc, s35, v25
	v_cndmask_b32_e64 v20, 0, v20, s[42:43]
	v_cndmask_b32_e64 v24, 0, v24, s[66:67]
	v_cndmask_b32_e64 v21, 0, v21, s[0:1]
	v_cndmask_b32_e32 v25, 0, v25, vcc
	v_max_u32_e32 v26, v18, v22
	v_max_u32_e32 v27, v19, v23
	v_max_u32_e32 v28, v20, v24
	v_max_u32_e32 v29, v21, v25
	v_max_u32_dpp v26, v26, v26 quad_perm:[1,0,3,2] row_mask:0xf bank_mask:0xf
	v_max_u32_dpp v27, v27, v27 quad_perm:[1,0,3,2] row_mask:0xf bank_mask:0xf
	v_max_u32_dpp v28, v28, v28 quad_perm:[1,0,3,2] row_mask:0xf bank_mask:0xf
	v_max_u32_dpp v29, v29, v29 quad_perm:[1,0,3,2] row_mask:0xf bank_mask:0xf
	v_max_u32_dpp v26, v26, v26 quad_perm:[2,3,0,1] row_mask:0xf bank_mask:0xf
	v_max_u32_dpp v27, v27, v27 quad_perm:[2,3,0,1] row_mask:0xf bank_mask:0xf
	v_max_u32_dpp v28, v28, v28 quad_perm:[2,3,0,1] row_mask:0xf bank_mask:0xf
	v_max_u32_dpp v29, v29, v29 quad_perm:[2,3,0,1] row_mask:0xf bank_mask:0xf
	v_max_u32_dpp v26, v26, v26 row_half_mirror row_mask:0xf bank_mask:0xf
	v_max_u32_dpp v27, v27, v27 row_half_mirror row_mask:0xf bank_mask:0xf
	v_max_u32_dpp v28, v28, v28 row_half_mirror row_mask:0xf bank_mask:0xf
	v_max_u32_dpp v29, v29, v29 row_half_mirror row_mask:0xf bank_mask:0xf
	v_max_u32_dpp v26, v26, v26 row_mirror row_mask:0xf bank_mask:0xf
	v_max_u32_dpp v27, v27, v27 row_mirror row_mask:0xf bank_mask:0xf
	v_max_u32_dpp v28, v28, v28 row_mirror row_mask:0xf bank_mask:0xf
	v_max_u32_dpp v29, v29, v29 row_mirror row_mask:0xf bank_mask:0xf
; __device__ __forceinline__ void nsa_quad_pre(int bg, int quad, const bf16_t* Q, const bf16_t* KV, const bf16_t* KCMP, const bf16_t* VCMPT, const float* GN, bf16_t* ONSA, ...
;     ...
;             for (int it = 0; it < 13; ++it) {
;                 unsigned m = k0 > k1 ? k0 : k1;
; #pragma unroll
;                 for (int off = 32; off >= 1; off >>= 1) { const unsigned o = (unsigned)__shfl_xor((int)m, off); m = o > m ? o : m; }
;                 if (k0 == m) k0 = 0u; if (k1 == m) k1 = 0u;
;                 if (lane == 0) selq[tt * 16 + it] = 127 - (int)(m & 127u);
	v_max_u32_dpp v26, v26, v26 row_bcast:15 row_mask:0xa bank_mask:0xf
	v_max_u32_dpp v27, v27, v27 row_bcast:15 row_mask:0xa bank_mask:0xf
	v_max_u32_dpp v28, v28, v28 row_bcast:15 row_mask:0xa bank_mask:0xf
	v_max_u32_dpp v29, v29, v29 row_bcast:15 row_mask:0xa bank_mask:0xf
	v_max_u32_dpp v26, v26, v26 row_bcast:31 row_mask:0xc bank_mask:0xf
	v_max_u32_dpp v27, v27, v27 row_bcast:31 row_mask:0xc bank_mask:0xf
	v_max_u32_dpp v28, v28, v28 row_bcast:31 row_mask:0xc bank_mask:0xf
	v_max_u32_dpp v29, v29, v29 row_bcast:31 row_mask:0xc bank_mask:0xf
	v_readlane_b32 s14, v26, 63
	v_readlane_b32 s15, v27, 63
	v_readlane_b32 s34, v28, 63
	v_readlane_b32 s35, v29, 63
	v_writelane_b32 v82, s14, 2
	v_writelane_b32 v83, s15, 2
	v_writelane_b32 v84, s34, 2
	v_writelane_b32 v85, s35, 2
	v_cmp_ne_u32_e64 s[42:43], s14, v18
	v_cmp_ne_u32_e64 s[66:67], s14, v22
	v_cmp_ne_u32_e64 s[0:1], s15, v19
	v_cmp_ne_u32_e32 vcc, s15, v23
	v_cndmask_b32_e64 v18, 0, v18, s[42:43]
	v_cndmask_b32_e64 v22, 0, v22, s[66:67]
	v_cndmask_b32_e64 v19, 0, v19, s[0:1]
	v_cndmask_b32_e32 v23, 0, v23, vcc
	v_cmp_ne_u32_e64 s[42:43], s34, v20
	v_cmp_ne_u32_e64 s[66:67], s34, v24
	v_cmp_ne_u32_e64 s[0:1], s35, v21
	v_cmp_ne_u32_e32 vcc, s35, v25
	v_cndmask_b32_e64 v20, 0, v20, s[42:43]
	v_cndmask_b32_e64 v24, 0, v24, s[66:67]
	v_cndmask_b32_e64 v21, 0, v21, s[0:1]
	v_cndmask_b32_e32 v25, 0, v25, vcc
	v_max_u32_e32 v26, v18, v22
	v_max_u32_e32 v27, v19, v23
	v_max_u32_e32 v28, v20, v24
	v_max_u32_e32 v29, v21, v25
	v_max_u32_dpp v26, v26, v26 quad_perm:[1,0,3,2] row_mask:0xf bank_mask:0xf
	v_max_u32_dpp v27, v27, v27 quad_perm:[1,0,3,2] row_mask:0xf bank_mask:0xf
	v_max_u32_dpp v28, v28, v28 quad_perm:[1,0,3,2] row_mask:0xf bank_mask:0xf
	v_max_u32_dpp v29, v29, v29 quad_perm:[1,0,3,2] row_mask:0xf bank_mask:0xf
	v_max_u32_dpp v26, v26, v26 quad_perm:[2,3,0,1] row_mask:0xf bank_mask:0xf
	v_max_u32_dpp v27, v27, v27 quad_perm:[2,3,0,1] row_mask:0xf bank_mask:0xf
	v_max_u32_dpp v28, v28, v28 quad_perm:[2,3,0,1] row_mask:0xf bank_mask:0xf
	v_max_u32_dpp v29, v29, v29 quad_perm:[2,3,0,1] row_mask:0xf bank_mask:0xf
	v_max_u32_dpp v26, v26, v26 row_half_mirror row_mask:0xf bank_mask:0xf
	v_max_u32_dpp v27, v27, v27 row_half_mirror row_mask:0xf bank_mask:0xf
	v_max_u32_dpp v28, v28, v28 row_half_mirror row_mask:0xf bank_mask:0xf
	v_max_u32_dpp v29, v29, v29 row_half_mirror row_mask:0xf bank_mask:0xf
	v_max_u32_dpp v26, v26, v26 row_mirror row_mask:0xf bank_mask:0xf
	v_max_u32_dpp v27, v27, v27 row_mirror row_mask:0xf bank_mask:0xf
	v_max_u32_dpp v28, v28, v28 row_mirror row_mask:0xf bank_mask:0xf
	v_max_u32_dpp v29, v29, v29 row_mirror row_mask:0xf bank_mask:0xf
	v_max_u32_dpp v26, v26, v26 row_bcast:15 row_mask:0xa bank_mask:0xf
	v_max_u32_dpp v27, v27, v27 row_bcast:15 row_mask:0xa bank_mask:0xf
	v_max_u32_dpp v28, v28, v28 row_bcast:15 row_mask:0xa bank_mask:0xf
	v_max_u32_dpp v29, v29, v29 row_bcast:15 row_mask:0xa bank_mask:0xf
	v_max_u32_dpp v26, v26, v26 row_bcast:31 row_mask:0xc bank_mask:0xf
	v_max_u32_dpp v27, v27, v27 row_bcast:31 row_mask:0xc bank_mask:0xf
	v_max_u32_dpp v28, v28, v28 row_bcast:31 row_mask:0xc bank_mask:0xf
	v_max_u32_dpp v29, v29, v29 row_bcast:31 row_mask:0xc bank_mask:0xf
	v_readlane_b32 s14, v26, 63
	v_readlane_b32 s15, v27, 63
	v_readlane_b32 s34, v28, 63
	v_readlane_b32 s35, v29, 63
	v_writelane_b32 v82, s14, 3
	v_writelane_b32 v83, s15, 3
	v_writelane_b32 v84, s34, 3
	v_writelane_b32 v85, s35, 3
	v_cmp_ne_u32_e64 s[42:43], s14, v18
	v_cmp_ne_u32_e64 s[66:67], s14, v22
	v_cmp_ne_u32_e64 s[0:1], s15, v19
	v_cmp_ne_u32_e32 vcc, s15, v23
	v_cndmask_b32_e64 v18, 0, v18, s[42:43]
	v_cndmask_b32_e64 v22, 0, v22, s[66:67]
	v_cndmask_b32_e64 v19, 0, v19, s[0:1]
	v_cndmask_b32_e32 v23, 0, v23, vcc
	v_cmp_ne_u32_e64 s[42:43], s34, v20
	v_cmp_ne_u32_e64 s[66:67], s34, v24
	v_cmp_ne_u32_e64 s[0:1], s35, v21
	v_cmp_ne_u32_e32 vcc, s35, v25
	v_cndmask_b32_e64 v20, 0, v20, s[42:43]
	v_cndmask_b32_e64 v24, 0, v24, s[66:67]
	v_cndmask_b32_e64 v21, 0, v21, s[0:1]
	v_cndmask_b32_e32 v25, 0, v25, vcc
	v_max_u32_e32 v26, v18, v22
	v_max_u32_e32 v27, v19, v23
	v_max_u32_e32 v28, v20, v24
	v_max_u32_e32 v29, v21, v25
	v_max_u32_dpp v26, v26, v26 quad_perm:[1,0,3,2] row_mask:0xf bank_mask:0xf
	v_max_u32_dpp v27, v27, v27 quad_perm:[1,0,3,2] row_mask:0xf bank_mask:0xf
	v_max_u32_dpp v28, v28, v28 quad_perm:[1,0,3,2] row_mask:0xf bank_mask:0xf
	v_max_u32_dpp v29, v29, v29 quad_perm:[1,0,3,2] row_mask:0xf bank_mask:0xf
	v_max_u32_dpp v26, v26, v26 quad_perm:[2,3,0,1] row_mask:0xf bank_mask:0xf
	v_max_u32_dpp v27, v27, v27 quad_perm:[2,3,0,1] row_mask:0xf bank_mask:0xf
	v_max_u32_dpp v28, v28, v28 quad_perm:[2,3,0,1] row_mask:0xf bank_mask:0xf
	v_max_u32_dpp v29, v29, v29 quad_perm:[2,3,0,1] row_mask:0xf bank_mask:0xf
	v_max_u32_dpp v26, v26, v26 row_half_mirror row_mask:0xf bank_mask:0xf
	v_max_u32_dpp v27, v27, v27 row_half_mirror row_mask:0xf bank_mask:0xf
	v_max_u32_dpp v28, v28, v28 row_half_mirror row_mask:0xf bank_mask:0xf
	v_max_u32_dpp v29, v29, v29 row_half_mirror row_mask:0xf bank_mask:0xf
	v_max_u32_dpp v26, v26, v26 row_mirror row_mask:0xf bank_mask:0xf
	v_max_u32_dpp v27, v27, v27 row_mirror row_mask:0xf bank_mask:0xf
	v_max_u32_dpp v28, v28, v28 row_mirror row_mask:0xf bank_mask:0xf
	v_max_u32_dpp v29, v29, v29 row_mirror row_mask:0xf bank_mask:0xf
	v_max_u32_dpp v26, v26, v26 row_bcast:15 row_mask:0xa bank_mask:0xf
	v_max_u32_dpp v27, v27, v27 row_bcast:15 row_mask:0xa bank_mask:0xf
	v_max_u32_dpp v28, v28, v28 row_bcast:15 row_mask:0xa bank_mask:0xf
	v_max_u32_dpp v29, v29, v29 row_bcast:15 row_mask:0xa bank_mask:0xf
	v_max_u32_dpp v26, v26, v26 row_bcast:31 row_mask:0xc bank_mask:0xf
; __device__ __forceinline__ void nsa_quad_pre(int bg, int quad, const bf16_t* Q, const bf16_t* KV, const bf16_t* KCMP, const bf16_t* VCMPT, const float* GN, bf16_t* ONSA, ...
;     ...
;             for (int it = 0; it < 13; ++it) {
;                 unsigned m = k0 > k1 ? k0 : k1;
; #pragma unroll
;                 for (int off = 32; off >= 1; off >>= 1) { const unsigned o = (unsigned)__shfl_xor((int)m, off); m = o > m ? o : m; }
;                 if (k0 == m) k0 = 0u; if (k1 == m) k1 = 0u;
;                 if (lane == 0) selq[tt * 16 + it] = 127 - (int)(m & 127u);
	v_max_u32_dpp v27, v27, v27 row_bcast:31 row_mask:0xc bank_mask:0xf
	v_max_u32_dpp v28, v28, v28 row_bcast:31 row_mask:0xc bank_mask:0xf
	v_max_u32_dpp v29, v29, v29 row_bcast:31 row_mask:0xc bank_mask:0xf
	v_readlane_b32 s14, v26, 63
	v_readlane_b32 s15, v27, 63
	v_readlane_b32 s34, v28, 63
	v_readlane_b32 s35, v29, 63
	v_writelane_b32 v82, s14, 4
	v_writelane_b32 v83, s15, 4
	v_writelane_b32 v84, s34, 4
	v_writelane_b32 v85, s35, 4
	v_cmp_ne_u32_e64 s[42:43], s14, v18
	v_cmp_ne_u32_e64 s[66:67], s14, v22
	v_cmp_ne_u32_e64 s[0:1], s15, v19
	v_cmp_ne_u32_e32 vcc, s15, v23
	v_cndmask_b32_e64 v18, 0, v18, s[42:43]
	v_cndmask_b32_e64 v22, 0, v22, s[66:67]
	v_cndmask_b32_e64 v19, 0, v19, s[0:1]
	v_cndmask_b32_e32 v23, 0, v23, vcc
	v_cmp_ne_u32_e64 s[42:43], s34, v20
	v_cmp_ne_u32_e64 s[66:67], s34, v24
	v_cmp_ne_u32_e64 s[0:1], s35, v21
	v_cmp_ne_u32_e32 vcc, s35, v25
	v_cndmask_b32_e64 v20, 0, v20, s[42:43]
	v_cndmask_b32_e64 v24, 0, v24, s[66:67]
	v_cndmask_b32_e64 v21, 0, v21, s[0:1]
	v_cndmask_b32_e32 v25, 0, v25, vcc
	v_max_u32_e32 v26, v18, v22
	v_max_u32_e32 v27, v19, v23
	v_max_u32_e32 v28, v20, v24
	v_max_u32_e32 v29, v21, v25
	v_max_u32_dpp v26, v26, v26 quad_perm:[1,0,3,2] row_mask:0xf bank_mask:0xf
	v_max_u32_dpp v27, v27, v27 quad_perm:[1,0,3,2] row_mask:0xf bank_mask:0xf
	v_max_u32_dpp v28, v28, v28 quad_perm:[1,0,3,2] row_mask:0xf bank_mask:0xf
	v_max_u32_dpp v29, v29, v29 quad_perm:[1,0,3,2] row_mask:0xf bank_mask:0xf
	v_max_u32_dpp v26, v26, v26 quad_perm:[2,3,0,1] row_mask:0xf bank_mask:0xf
	v_max_u32_dpp v27, v27, v27 quad_perm:[2,3,0,1] row_mask:0xf bank_mask:0xf
	v_max_u32_dpp v28, v28, v28 quad_perm:[2,3,0,1] row_mask:0xf bank_mask:0xf
	v_max_u32_dpp v29, v29, v29 quad_perm:[2,3,0,1] row_mask:0xf bank_mask:0xf
	v_max_u32_dpp v26, v26, v26 row_half_mirror row_mask:0xf bank_mask:0xf
	v_max_u32_dpp v27, v27, v27 row_half_mirror row_mask:0xf bank_mask:0xf
	v_max_u32_dpp v28, v28, v28 row_half_mirror row_mask:0xf bank_mask:0xf
	v_max_u32_dpp v29, v29, v29 row_half_mirror row_mask:0xf bank_mask:0xf
	v_max_u32_dpp v26, v26, v26 row_mirror row_mask:0xf bank_mask:0xf
	v_max_u32_dpp v27, v27, v27 row_mirror row_mask:0xf bank_mask:0xf
	v_max_u32_dpp v28, v28, v28 row_mirror row_mask:0xf bank_mask:0xf
	v_max_u32_dpp v29, v29, v29 row_mirror row_mask:0xf bank_mask:0xf
	v_max_u32_dpp v26, v26, v26 row_bcast:15 row_mask:0xa bank_mask:0xf
	v_max_u32_dpp v27, v27, v27 row_bcast:15 row_mask:0xa bank_mask:0xf
	v_max_u32_dpp v28, v28, v28 row_bcast:15 row_mask:0xa bank_mask:0xf
	v_max_u32_dpp v29, v29, v29 row_bcast:15 row_mask:0xa bank_mask:0xf
	v_max_u32_dpp v26, v26, v26 row_bcast:31 row_mask:0xc bank_mask:0xf
	v_max_u32_dpp v27, v27, v27 row_bcast:31 row_mask:0xc bank_mask:0xf
	v_max_u32_dpp v28, v28, v28 row_bcast:31 row_mask:0xc bank_mask:0xf
	v_max_u32_dpp v29, v29, v29 row_bcast:31 row_mask:0xc bank_mask:0xf
	v_readlane_b32 s14, v26, 63
	v_readlane_b32 s15, v27, 63
	v_readlane_b32 s34, v28, 63
	v_readlane_b32 s35, v29, 63
	v_writelane_b32 v82, s14, 5
	v_writelane_b32 v83, s15, 5
	v_writelane_b32 v84, s34, 5
	v_writelane_b32 v85, s35, 5
	v_cmp_ne_u32_e64 s[42:43], s14, v18
	v_cmp_ne_u32_e64 s[66:67], s14, v22
	v_cmp_ne_u32_e64 s[0:1], s15, v19
	v_cmp_ne_u32_e32 vcc, s15, v23
	v_cndmask_b32_e64 v18, 0, v18, s[42:43]
	v_cndmask_b32_e64 v22, 0, v22, s[66:67]
	v_cndmask_b32_e64 v19, 0, v19, s[0:1]
	v_cndmask_b32_e32 v23, 0, v23, vcc
	v_cmp_ne_u32_e64 s[42:43], s34, v20
	v_cmp_ne_u32_e64 s[66:67], s34, v24
	v_cmp_ne_u32_e64 s[0:1], s35, v21
	v_cmp_ne_u32_e32 vcc, s35, v25
	v_cndmask_b32_e64 v20, 0, v20, s[42:43]
	v_cndmask_b32_e64 v24, 0, v24, s[66:67]
	v_cndmask_b32_e64 v21, 0, v21, s[0:1]
	v_cndmask_b32_e32 v25, 0, v25, vcc
	v_max_u32_e32 v26, v18, v22
	v_max_u32_e32 v27, v19, v23
	v_max_u32_e32 v28, v20, v24
	v_max_u32_e32 v29, v21, v25
	v_max_u32_dpp v26, v26, v26 quad_perm:[1,0,3,2] row_mask:0xf bank_mask:0xf
	v_max_u32_dpp v27, v27, v27 quad_perm:[1,0,3,2] row_mask:0xf bank_mask:0xf
	v_max_u32_dpp v28, v28, v28 quad_perm:[1,0,3,2] row_mask:0xf bank_mask:0xf
	v_max_u32_dpp v29, v29, v29 quad_perm:[1,0,3,2] row_mask:0xf bank_mask:0xf
	v_max_u32_dpp v26, v26, v26 quad_perm:[2,3,0,1] row_mask:0xf bank_mask:0xf
	v_max_u32_dpp v27, v27, v27 quad_perm:[2,3,0,1] row_mask:0xf bank_mask:0xf
	v_max_u32_dpp v28, v28, v28 quad_perm:[2,3,0,1] row_mask:0xf bank_mask:0xf
	v_max_u32_dpp v29, v29, v29 quad_perm:[2,3,0,1] row_mask:0xf bank_mask:0xf
	v_max_u32_dpp v26, v26, v26 row_half_mirror row_mask:0xf bank_mask:0xf
	v_max_u32_dpp v27, v27, v27 row_half_mirror row_mask:0xf bank_mask:0xf
	v_max_u32_dpp v28, v28, v28 row_half_mirror row_mask:0xf bank_mask:0xf
	v_max_u32_dpp v29, v29, v29 row_half_mirror row_mask:0xf bank_mask:0xf
	v_max_u32_dpp v26, v26, v26 row_mirror row_mask:0xf bank_mask:0xf
	v_max_u32_dpp v27, v27, v27 row_mirror row_mask:0xf bank_mask:0xf
	v_max_u32_dpp v28, v28, v28 row_mirror row_mask:0xf bank_mask:0xf
	v_max_u32_dpp v29, v29, v29 row_mirror row_mask:0xf bank_mask:0xf
	v_max_u32_dpp v26, v26, v26 row_bcast:15 row_mask:0xa bank_mask:0xf
	v_max_u32_dpp v27, v27, v27 row_bcast:15 row_mask:0xa bank_mask:0xf
	v_max_u32_dpp v28, v28, v28 row_bcast:15 row_mask:0xa bank_mask:0xf
	v_max_u32_dpp v29, v29, v29 row_bcast:15 row_mask:0xa bank_mask:0xf
	v_max_u32_dpp v26, v26, v26 row_bcast:31 row_mask:0xc bank_mask:0xf
	v_max_u32_dpp v27, v27, v27 row_bcast:31 row_mask:0xc bank_mask:0xf
	v_max_u32_dpp v28, v28, v28 row_bcast:31 row_mask:0xc bank_mask:0xf
	v_max_u32_dpp v29, v29, v29 row_bcast:31 row_mask:0xc bank_mask:0xf
	v_readlane_b32 s14, v26, 63
	v_readlane_b32 s15, v27, 63
	v_readlane_b32 s34, v28, 63
	v_readlane_b32 s35, v29, 63
; __device__ __forceinline__ void nsa_quad_pre(int bg, int quad, const bf16_t* Q, const bf16_t* KV, const bf16_t* KCMP, const bf16_t* VCMPT, const float* GN, bf16_t* ONSA, ...
;     ...
;             for (int it = 0; it < 13; ++it) {
;                 unsigned m = k0 > k1 ? k0 : k1;
; #pragma unroll
;                 for (int off = 32; off >= 1; off >>= 1) { const unsigned o = (unsigned)__shfl_xor((int)m, off); m = o > m ? o : m; }
;                 if (k0 == m) k0 = 0u; if (k1 == m) k1 = 0u;
;                 if (lane == 0) selq[tt * 16 + it] = 127 - (int)(m & 127u);
	v_writelane_b32 v82, s14, 6
	v_writelane_b32 v83, s15, 6
	v_writelane_b32 v84, s34, 6
	v_writelane_b32 v85, s35, 6
	v_cmp_ne_u32_e64 s[42:43], s14, v18
	v_cmp_ne_u32_e64 s[66:67], s14, v22
	v_cmp_ne_u32_e64 s[0:1], s15, v19
	v_cmp_ne_u32_e32 vcc, s15, v23
	v_cndmask_b32_e64 v18, 0, v18, s[42:43]
	v_cndmask_b32_e64 v22, 0, v22, s[66:67]
	v_cndmask_b32_e64 v19, 0, v19, s[0:1]
	v_cndmask_b32_e32 v23, 0, v23, vcc
	v_cmp_ne_u32_e64 s[42:43], s34, v20
	v_cmp_ne_u32_e64 s[66:67], s34, v24
	v_cmp_ne_u32_e64 s[0:1], s35, v21
	v_cmp_ne_u32_e32 vcc, s35, v25
	v_cndmask_b32_e64 v20, 0, v20, s[42:43]
	v_cndmask_b32_e64 v24, 0, v24, s[66:67]
	v_cndmask_b32_e64 v21, 0, v21, s[0:1]
	v_cndmask_b32_e32 v25, 0, v25, vcc
	v_max_u32_e32 v26, v18, v22
	v_max_u32_e32 v27, v19, v23
	v_max_u32_e32 v28, v20, v24
	v_max_u32_e32 v29, v21, v25
	v_max_u32_dpp v26, v26, v26 quad_perm:[1,0,3,2] row_mask:0xf bank_mask:0xf
	v_max_u32_dpp v27, v27, v27 quad_perm:[1,0,3,2] row_mask:0xf bank_mask:0xf
	v_max_u32_dpp v28, v28, v28 quad_perm:[1,0,3,2] row_mask:0xf bank_mask:0xf
	v_max_u32_dpp v29, v29, v29 quad_perm:[1,0,3,2] row_mask:0xf bank_mask:0xf
	v_max_u32_dpp v26, v26, v26 quad_perm:[2,3,0,1] row_mask:0xf bank_mask:0xf
	v_max_u32_dpp v27, v27, v27 quad_perm:[2,3,0,1] row_mask:0xf bank_mask:0xf
	v_max_u32_dpp v28, v28, v28 quad_perm:[2,3,0,1] row_mask:0xf bank_mask:0xf
	v_max_u32_dpp v29, v29, v29 quad_perm:[2,3,0,1] row_mask:0xf bank_mask:0xf
	v_max_u32_dpp v26, v26, v26 row_half_mirror row_mask:0xf bank_mask:0xf
	v_max_u32_dpp v27, v27, v27 row_half_mirror row_mask:0xf bank_mask:0xf
	v_max_u32_dpp v28, v28, v28 row_half_mirror row_mask:0xf bank_mask:0xf
	v_max_u32_dpp v29, v29, v29 row_half_mirror row_mask:0xf bank_mask:0xf
	v_max_u32_dpp v26, v26, v26 row_mirror row_mask:0xf bank_mask:0xf
	v_max_u32_dpp v27, v27, v27 row_mirror row_mask:0xf bank_mask:0xf
	v_max_u32_dpp v28, v28, v28 row_mirror row_mask:0xf bank_mask:0xf
	v_max_u32_dpp v29, v29, v29 row_mirror row_mask:0xf bank_mask:0xf
	v_max_u32_dpp v26, v26, v26 row_bcast:15 row_mask:0xa bank_mask:0xf
	v_max_u32_dpp v27, v27, v27 row_bcast:15 row_mask:0xa bank_mask:0xf
	v_max_u32_dpp v28, v28, v28 row_bcast:15 row_mask:0xa bank_mask:0xf
	v_max_u32_dpp v29, v29, v29 row_bcast:15 row_mask:0xa bank_mask:0xf
	v_max_u32_dpp v26, v26, v26 row_bcast:31 row_mask:0xc bank_mask:0xf
	v_max_u32_dpp v27, v27, v27 row_bcast:31 row_mask:0xc bank_mask:0xf
	v_max_u32_dpp v28, v28, v28 row_bcast:31 row_mask:0xc bank_mask:0xf
	v_max_u32_dpp v29, v29, v29 row_bcast:31 row_mask:0xc bank_mask:0xf
	v_readlane_b32 s14, v26, 63
	v_readlane_b32 s15, v27, 63
	v_readlane_b32 s34, v28, 63
	v_readlane_b32 s35, v29, 63
	v_writelane_b32 v82, s14, 7
	v_writelane_b32 v83, s15, 7
	v_writelane_b32 v84, s34, 7
	v_writelane_b32 v85, s35, 7
	v_cmp_ne_u32_e64 s[42:43], s14, v18
	v_cmp_ne_u32_e64 s[66:67], s14, v22
	v_cmp_ne_u32_e64 s[0:1], s15, v19
	v_cmp_ne_u32_e32 vcc, s15, v23
	v_cndmask_b32_e64 v18, 0, v18, s[42:43]
	v_cndmask_b32_e64 v22, 0, v22, s[66:67]
	v_cndmask_b32_e64 v19, 0, v19, s[0:1]
	v_cndmask_b32_e32 v23, 0, v23, vcc
	v_cmp_ne_u32_e64 s[42:43], s34, v20
	v_cmp_ne_u32_e64 s[66:67], s34, v24
	v_cmp_ne_u32_e64 s[0:1], s35, v21
	v_cmp_ne_u32_e32 vcc, s35, v25
	v_cndmask_b32_e64 v20, 0, v20, s[42:43]
	v_cndmask_b32_e64 v24, 0, v24, s[66:67]
	v_cndmask_b32_e64 v21, 0, v21, s[0:1]
	v_cndmask_b32_e32 v25, 0, v25, vcc
	v_max_u32_e32 v26, v18, v22
	v_max_u32_e32 v27, v19, v23
	v_max_u32_e32 v28, v20, v24
	v_max_u32_e32 v29, v21, v25
	v_max_u32_dpp v26, v26, v26 quad_perm:[1,0,3,2] row_mask:0xf bank_mask:0xf
	v_max_u32_dpp v27, v27, v27 quad_perm:[1,0,3,2] row_mask:0xf bank_mask:0xf
	v_max_u32_dpp v28, v28, v28 quad_perm:[1,0,3,2] row_mask:0xf bank_mask:0xf
	v_max_u32_dpp v29, v29, v29 quad_perm:[1,0,3,2] row_mask:0xf bank_mask:0xf
	v_max_u32_dpp v26, v26, v26 quad_perm:[2,3,0,1] row_mask:0xf bank_mask:0xf
	v_max_u32_dpp v27, v27, v27 quad_perm:[2,3,0,1] row_mask:0xf bank_mask:0xf
	v_max_u32_dpp v28, v28, v28 quad_perm:[2,3,0,1] row_mask:0xf bank_mask:0xf
	v_max_u32_dpp v29, v29, v29 quad_perm:[2,3,0,1] row_mask:0xf bank_mask:0xf
	v_max_u32_dpp v26, v26, v26 row_half_mirror row_mask:0xf bank_mask:0xf
	v_max_u32_dpp v27, v27, v27 row_half_mirror row_mask:0xf bank_mask:0xf
	v_max_u32_dpp v28, v28, v28 row_half_mirror row_mask:0xf bank_mask:0xf
	v_max_u32_dpp v29, v29, v29 row_half_mirror row_mask:0xf bank_mask:0xf
	v_max_u32_dpp v26, v26, v26 row_mirror row_mask:0xf bank_mask:0xf
	v_max_u32_dpp v27, v27, v27 row_mirror row_mask:0xf bank_mask:0xf
	v_max_u32_dpp v28, v28, v28 row_mirror row_mask:0xf bank_mask:0xf
	v_max_u32_dpp v29, v29, v29 row_mirror row_mask:0xf bank_mask:0xf
	v_max_u32_dpp v26, v26, v26 row_bcast:15 row_mask:0xa bank_mask:0xf
	v_max_u32_dpp v27, v27, v27 row_bcast:15 row_mask:0xa bank_mask:0xf
	v_max_u32_dpp v28, v28, v28 row_bcast:15 row_mask:0xa bank_mask:0xf
	v_max_u32_dpp v29, v29, v29 row_bcast:15 row_mask:0xa bank_mask:0xf
	v_max_u32_dpp v26, v26, v26 row_bcast:31 row_mask:0xc bank_mask:0xf
	v_max_u32_dpp v27, v27, v27 row_bcast:31 row_mask:0xc bank_mask:0xf
	v_max_u32_dpp v28, v28, v28 row_bcast:31 row_mask:0xc bank_mask:0xf
	v_max_u32_dpp v29, v29, v29 row_bcast:31 row_mask:0xc bank_mask:0xf
	v_readlane_b32 s14, v26, 63
	v_readlane_b32 s15, v27, 63
	v_readlane_b32 s34, v28, 63
	v_readlane_b32 s35, v29, 63
	v_writelane_b32 v82, s14, 8
	v_writelane_b32 v83, s15, 8
	v_writelane_b32 v84, s34, 8
	v_writelane_b32 v85, s35, 8
	v_cmp_ne_u32_e64 s[42:43], s14, v18
	v_cmp_ne_u32_e64 s[66:67], s14, v22
	v_cmp_ne_u32_e64 s[0:1], s15, v19
	v_cmp_ne_u32_e32 vcc, s15, v23
	v_cndmask_b32_e64 v18, 0, v18, s[42:43]
	v_cndmask_b32_e64 v22, 0, v22, s[66:67]
; __device__ __forceinline__ void nsa_quad_pre(int bg, int quad, const bf16_t* Q, const bf16_t* KV, const bf16_t* KCMP, const bf16_t* VCMPT, const float* GN, bf16_t* ONSA, ...
;     ...
;             for (int it = 0; it < 13; ++it) {
;                 unsigned m = k0 > k1 ? k0 : k1;
; #pragma unroll
;                 for (int off = 32; off >= 1; off >>= 1) { const unsigned o = (unsigned)__shfl_xor((int)m, off); m = o > m ? o : m; }
;                 if (k0 == m) k0 = 0u; if (k1 == m) k1 = 0u;
;                 if (lane == 0) selq[tt * 16 + it] = 127 - (int)(m & 127u);
	v_cndmask_b32_e64 v19, 0, v19, s[0:1]
	v_cndmask_b32_e32 v23, 0, v23, vcc
	v_cmp_ne_u32_e64 s[42:43], s34, v20
	v_cmp_ne_u32_e64 s[66:67], s34, v24
	v_cmp_ne_u32_e64 s[0:1], s35, v21
	v_cmp_ne_u32_e32 vcc, s35, v25
	v_cndmask_b32_e64 v20, 0, v20, s[42:43]
	v_cndmask_b32_e64 v24, 0, v24, s[66:67]
	v_cndmask_b32_e64 v21, 0, v21, s[0:1]
	v_cndmask_b32_e32 v25, 0, v25, vcc
	v_max_u32_e32 v26, v18, v22
	v_max_u32_e32 v27, v19, v23
	v_max_u32_e32 v28, v20, v24
	v_max_u32_e32 v29, v21, v25
	v_max_u32_dpp v26, v26, v26 quad_perm:[1,0,3,2] row_mask:0xf bank_mask:0xf
	v_max_u32_dpp v27, v27, v27 quad_perm:[1,0,3,2] row_mask:0xf bank_mask:0xf
	v_max_u32_dpp v28, v28, v28 quad_perm:[1,0,3,2] row_mask:0xf bank_mask:0xf
	v_max_u32_dpp v29, v29, v29 quad_perm:[1,0,3,2] row_mask:0xf bank_mask:0xf
	v_max_u32_dpp v26, v26, v26 quad_perm:[2,3,0,1] row_mask:0xf bank_mask:0xf
	v_max_u32_dpp v27, v27, v27 quad_perm:[2,3,0,1] row_mask:0xf bank_mask:0xf
	v_max_u32_dpp v28, v28, v28 quad_perm:[2,3,0,1] row_mask:0xf bank_mask:0xf
	v_max_u32_dpp v29, v29, v29 quad_perm:[2,3,0,1] row_mask:0xf bank_mask:0xf
	v_max_u32_dpp v26, v26, v26 row_half_mirror row_mask:0xf bank_mask:0xf
	v_max_u32_dpp v27, v27, v27 row_half_mirror row_mask:0xf bank_mask:0xf
	v_max_u32_dpp v28, v28, v28 row_half_mirror row_mask:0xf bank_mask:0xf
	v_max_u32_dpp v29, v29, v29 row_half_mirror row_mask:0xf bank_mask:0xf
	v_max_u32_dpp v26, v26, v26 row_mirror row_mask:0xf bank_mask:0xf
	v_max_u32_dpp v27, v27, v27 row_mirror row_mask:0xf bank_mask:0xf
	v_max_u32_dpp v28, v28, v28 row_mirror row_mask:0xf bank_mask:0xf
	v_max_u32_dpp v29, v29, v29 row_mirror row_mask:0xf bank_mask:0xf
	v_max_u32_dpp v26, v26, v26 row_bcast:15 row_mask:0xa bank_mask:0xf
	v_max_u32_dpp v27, v27, v27 row_bcast:15 row_mask:0xa bank_mask:0xf
	v_max_u32_dpp v28, v28, v28 row_bcast:15 row_mask:0xa bank_mask:0xf
	v_max_u32_dpp v29, v29, v29 row_bcast:15 row_mask:0xa bank_mask:0xf
	v_max_u32_dpp v26, v26, v26 row_bcast:31 row_mask:0xc bank_mask:0xf
	v_max_u32_dpp v27, v27, v27 row_bcast:31 row_mask:0xc bank_mask:0xf
	v_max_u32_dpp v28, v28, v28 row_bcast:31 row_mask:0xc bank_mask:0xf
	v_max_u32_dpp v29, v29, v29 row_bcast:31 row_mask:0xc bank_mask:0xf
	v_readlane_b32 s14, v26, 63
	v_readlane_b32 s15, v27, 63
	v_readlane_b32 s34, v28, 63
	v_readlane_b32 s35, v29, 63
	v_writelane_b32 v82, s14, 9
	v_writelane_b32 v83, s15, 9
	v_writelane_b32 v84, s34, 9
	v_writelane_b32 v85, s35, 9
	v_cmp_ne_u32_e64 s[42:43], s14, v18
	v_cmp_ne_u32_e64 s[66:67], s14, v22
	v_cmp_ne_u32_e64 s[0:1], s15, v19
	v_cmp_ne_u32_e32 vcc, s15, v23
	v_cndmask_b32_e64 v18, 0, v18, s[42:43]
	v_cndmask_b32_e64 v22, 0, v22, s[66:67]
	v_cndmask_b32_e64 v19, 0, v19, s[0:1]
	v_cndmask_b32_e32 v23, 0, v23, vcc
	v_cmp_ne_u32_e64 s[42:43], s34, v20
	v_cmp_ne_u32_e64 s[66:67], s34, v24
	v_cmp_ne_u32_e64 s[0:1], s35, v21
	v_cmp_ne_u32_e32 vcc, s35, v25
	v_cndmask_b32_e64 v20, 0, v20, s[42:43]
	v_cndmask_b32_e64 v24, 0, v24, s[66:67]
	v_cndmask_b32_e64 v21, 0, v21, s[0:1]
	v_cndmask_b32_e32 v25, 0, v25, vcc
	v_max_u32_e32 v26, v18, v22
	v_max_u32_e32 v27, v19, v23
	v_max_u32_e32 v28, v20, v24
	v_max_u32_e32 v29, v21, v25
	v_max_u32_dpp v26, v26, v26 quad_perm:[1,0,3,2] row_mask:0xf bank_mask:0xf
	v_max_u32_dpp v27, v27, v27 quad_perm:[1,0,3,2] row_mask:0xf bank_mask:0xf
	v_max_u32_dpp v28, v28, v28 quad_perm:[1,0,3,2] row_mask:0xf bank_mask:0xf
	v_max_u32_dpp v29, v29, v29 quad_perm:[1,0,3,2] row_mask:0xf bank_mask:0xf
	v_max_u32_dpp v26, v26, v26 quad_perm:[2,3,0,1] row_mask:0xf bank_mask:0xf
	v_max_u32_dpp v27, v27, v27 quad_perm:[2,3,0,1] row_mask:0xf bank_mask:0xf
	v_max_u32_dpp v28, v28, v28 quad_perm:[2,3,0,1] row_mask:0xf bank_mask:0xf
	v_max_u32_dpp v29, v29, v29 quad_perm:[2,3,0,1] row_mask:0xf bank_mask:0xf
	v_max_u32_dpp v26, v26, v26 row_half_mirror row_mask:0xf bank_mask:0xf
	v_max_u32_dpp v27, v27, v27 row_half_mirror row_mask:0xf bank_mask:0xf
	v_max_u32_dpp v28, v28, v28 row_half_mirror row_mask:0xf bank_mask:0xf
	v_max_u32_dpp v29, v29, v29 row_half_mirror row_mask:0xf bank_mask:0xf
	v_max_u32_dpp v26, v26, v26 row_mirror row_mask:0xf bank_mask:0xf
	v_max_u32_dpp v27, v27, v27 row_mirror row_mask:0xf bank_mask:0xf
	v_max_u32_dpp v28, v28, v28 row_mirror row_mask:0xf bank_mask:0xf
	v_max_u32_dpp v29, v29, v29 row_mirror row_mask:0xf bank_mask:0xf
	v_max_u32_dpp v26, v26, v26 row_bcast:15 row_mask:0xa bank_mask:0xf
	v_max_u32_dpp v27, v27, v27 row_bcast:15 row_mask:0xa bank_mask:0xf
	v_max_u32_dpp v28, v28, v28 row_bcast:15 row_mask:0xa bank_mask:0xf
	v_max_u32_dpp v29, v29, v29 row_bcast:15 row_mask:0xa bank_mask:0xf
	v_max_u32_dpp v26, v26, v26 row_bcast:31 row_mask:0xc bank_mask:0xf
	v_max_u32_dpp v27, v27, v27 row_bcast:31 row_mask:0xc bank_mask:0xf
	v_max_u32_dpp v28, v28, v28 row_bcast:31 row_mask:0xc bank_mask:0xf
	v_max_u32_dpp v29, v29, v29 row_bcast:31 row_mask:0xc bank_mask:0xf
	v_readlane_b32 s14, v26, 63
	v_readlane_b32 s15, v27, 63
	v_readlane_b32 s34, v28, 63
	v_readlane_b32 s35, v29, 63
	v_writelane_b32 v82, s14, 10
	v_writelane_b32 v83, s15, 10
	v_writelane_b32 v84, s34, 10
	v_writelane_b32 v85, s35, 10
	v_cmp_ne_u32_e64 s[42:43], s14, v18
	v_cmp_ne_u32_e64 s[66:67], s14, v22
	v_cmp_ne_u32_e64 s[0:1], s15, v19
	v_cmp_ne_u32_e32 vcc, s15, v23
	v_cndmask_b32_e64 v18, 0, v18, s[42:43]
	v_cndmask_b32_e64 v22, 0, v22, s[66:67]
	v_cndmask_b32_e64 v19, 0, v19, s[0:1]
	v_cndmask_b32_e32 v23, 0, v23, vcc
	v_cmp_ne_u32_e64 s[42:43], s34, v20
	v_cmp_ne_u32_e64 s[66:67], s34, v24
	v_cmp_ne_u32_e64 s[0:1], s35, v21
	v_cmp_ne_u32_e32 vcc, s35, v25
	v_cndmask_b32_e64 v20, 0, v20, s[42:43]
	v_cndmask_b32_e64 v24, 0, v24, s[66:67]
; __device__ __forceinline__ void nsa_quad_pre(int bg, int quad, const bf16_t* Q, const bf16_t* KV, const bf16_t* KCMP, const bf16_t* VCMPT, const float* GN, bf16_t* ONSA, ...
;     ...
;             for (int it = 0; it < 13; ++it) {
;                 unsigned m = k0 > k1 ? k0 : k1;
; #pragma unroll
;                 for (int off = 32; off >= 1; off >>= 1) { const unsigned o = (unsigned)__shfl_xor((int)m, off); m = o > m ? o : m; }
;                 if (k0 == m) k0 = 0u; if (k1 == m) k1 = 0u;
;                 if (lane == 0) selq[tt * 16 + it] = 127 - (int)(m & 127u);
;             }
;             if (lane == 0) { selq[tt * 16 + 13] = 0; selq[tt * 16 + 14] = cur - 1; selq[tt * 16 + 15] = cur; }
	v_cndmask_b32_e64 v21, 0, v21, s[0:1]
	v_cndmask_b32_e32 v25, 0, v25, vcc
	v_max_u32_e32 v26, v18, v22
	v_max_u32_e32 v27, v19, v23
	v_max_u32_e32 v28, v20, v24
	v_max_u32_e32 v29, v21, v25
	v_max_u32_dpp v26, v26, v26 quad_perm:[1,0,3,2] row_mask:0xf bank_mask:0xf
	v_max_u32_dpp v27, v27, v27 quad_perm:[1,0,3,2] row_mask:0xf bank_mask:0xf
	v_max_u32_dpp v28, v28, v28 quad_perm:[1,0,3,2] row_mask:0xf bank_mask:0xf
	v_max_u32_dpp v29, v29, v29 quad_perm:[1,0,3,2] row_mask:0xf bank_mask:0xf
	v_max_u32_dpp v26, v26, v26 quad_perm:[2,3,0,1] row_mask:0xf bank_mask:0xf
	v_max_u32_dpp v27, v27, v27 quad_perm:[2,3,0,1] row_mask:0xf bank_mask:0xf
	v_max_u32_dpp v28, v28, v28 quad_perm:[2,3,0,1] row_mask:0xf bank_mask:0xf
	v_max_u32_dpp v29, v29, v29 quad_perm:[2,3,0,1] row_mask:0xf bank_mask:0xf
	v_max_u32_dpp v26, v26, v26 row_half_mirror row_mask:0xf bank_mask:0xf
	v_max_u32_dpp v27, v27, v27 row_half_mirror row_mask:0xf bank_mask:0xf
	v_max_u32_dpp v28, v28, v28 row_half_mirror row_mask:0xf bank_mask:0xf
	v_max_u32_dpp v29, v29, v29 row_half_mirror row_mask:0xf bank_mask:0xf
	v_max_u32_dpp v26, v26, v26 row_mirror row_mask:0xf bank_mask:0xf
	v_max_u32_dpp v27, v27, v27 row_mirror row_mask:0xf bank_mask:0xf
	v_max_u32_dpp v28, v28, v28 row_mirror row_mask:0xf bank_mask:0xf
	v_max_u32_dpp v29, v29, v29 row_mirror row_mask:0xf bank_mask:0xf
	v_max_u32_dpp v26, v26, v26 row_bcast:15 row_mask:0xa bank_mask:0xf
	v_max_u32_dpp v27, v27, v27 row_bcast:15 row_mask:0xa bank_mask:0xf
	v_max_u32_dpp v28, v28, v28 row_bcast:15 row_mask:0xa bank_mask:0xf
	v_max_u32_dpp v29, v29, v29 row_bcast:15 row_mask:0xa bank_mask:0xf
	v_max_u32_dpp v26, v26, v26 row_bcast:31 row_mask:0xc bank_mask:0xf
	v_max_u32_dpp v27, v27, v27 row_bcast:31 row_mask:0xc bank_mask:0xf
	v_max_u32_dpp v28, v28, v28 row_bcast:31 row_mask:0xc bank_mask:0xf
	v_max_u32_dpp v29, v29, v29 row_bcast:31 row_mask:0xc bank_mask:0xf
	v_readlane_b32 s14, v26, 63
	v_readlane_b32 s15, v27, 63
	v_readlane_b32 s34, v28, 63
	v_readlane_b32 s35, v29, 63
	v_writelane_b32 v82, s14, 11
	v_writelane_b32 v83, s15, 11
	v_writelane_b32 v84, s34, 11
	v_writelane_b32 v85, s35, 11
	v_cmp_ne_u32_e64 s[42:43], s14, v18
	v_cmp_ne_u32_e64 s[66:67], s14, v22
	v_cmp_ne_u32_e64 s[0:1], s15, v19
	v_cmp_ne_u32_e32 vcc, s15, v23
	v_cndmask_b32_e64 v18, 0, v18, s[42:43]
	v_cndmask_b32_e64 v22, 0, v22, s[66:67]
	v_cndmask_b32_e64 v19, 0, v19, s[0:1]
	v_cndmask_b32_e32 v23, 0, v23, vcc
	v_cmp_ne_u32_e64 s[42:43], s34, v20
	v_cmp_ne_u32_e64 s[66:67], s34, v24
	v_cmp_ne_u32_e64 s[0:1], s35, v21
	v_cmp_ne_u32_e32 vcc, s35, v25
	v_cndmask_b32_e64 v20, 0, v20, s[42:43]
	v_cndmask_b32_e64 v24, 0, v24, s[66:67]
	v_cndmask_b32_e64 v21, 0, v21, s[0:1]
	v_cndmask_b32_e32 v25, 0, v25, vcc
	v_max_u32_e32 v26, v18, v22
	v_max_u32_e32 v27, v19, v23
	v_max_u32_e32 v28, v20, v24
	v_max_u32_e32 v29, v21, v25
	v_max_u32_dpp v26, v26, v26 quad_perm:[1,0,3,2] row_mask:0xf bank_mask:0xf
	v_max_u32_dpp v27, v27, v27 quad_perm:[1,0,3,2] row_mask:0xf bank_mask:0xf
	v_max_u32_dpp v28, v28, v28 quad_perm:[1,0,3,2] row_mask:0xf bank_mask:0xf
	v_max_u32_dpp v29, v29, v29 quad_perm:[1,0,3,2] row_mask:0xf bank_mask:0xf
	v_max_u32_dpp v26, v26, v26 quad_perm:[2,3,0,1] row_mask:0xf bank_mask:0xf
	v_max_u32_dpp v27, v27, v27 quad_perm:[2,3,0,1] row_mask:0xf bank_mask:0xf
	v_max_u32_dpp v28, v28, v28 quad_perm:[2,3,0,1] row_mask:0xf bank_mask:0xf
	v_max_u32_dpp v29, v29, v29 quad_perm:[2,3,0,1] row_mask:0xf bank_mask:0xf
	v_max_u32_dpp v26, v26, v26 row_half_mirror row_mask:0xf bank_mask:0xf
	v_max_u32_dpp v27, v27, v27 row_half_mirror row_mask:0xf bank_mask:0xf
	v_max_u32_dpp v28, v28, v28 row_half_mirror row_mask:0xf bank_mask:0xf
	v_max_u32_dpp v29, v29, v29 row_half_mirror row_mask:0xf bank_mask:0xf
	v_max_u32_dpp v26, v26, v26 row_mirror row_mask:0xf bank_mask:0xf
	v_max_u32_dpp v27, v27, v27 row_mirror row_mask:0xf bank_mask:0xf
	v_max_u32_dpp v28, v28, v28 row_mirror row_mask:0xf bank_mask:0xf
	v_max_u32_dpp v29, v29, v29 row_mirror row_mask:0xf bank_mask:0xf
	v_max_u32_dpp v26, v26, v26 row_bcast:15 row_mask:0xa bank_mask:0xf
	v_max_u32_dpp v27, v27, v27 row_bcast:15 row_mask:0xa bank_mask:0xf
	v_max_u32_dpp v28, v28, v28 row_bcast:15 row_mask:0xa bank_mask:0xf
	v_max_u32_dpp v29, v29, v29 row_bcast:15 row_mask:0xa bank_mask:0xf
	v_max_u32_dpp v26, v26, v26 row_bcast:31 row_mask:0xc bank_mask:0xf
	v_max_u32_dpp v27, v27, v27 row_bcast:31 row_mask:0xc bank_mask:0xf
	v_max_u32_dpp v28, v28, v28 row_bcast:31 row_mask:0xc bank_mask:0xf
	v_max_u32_dpp v29, v29, v29 row_bcast:31 row_mask:0xc bank_mask:0xf
	v_readlane_b32 s14, v26, 63
	v_readlane_b32 s15, v27, 63
	v_readlane_b32 s34, v28, 63
	v_readlane_b32 s35, v29, 63
	v_writelane_b32 v82, s14, 12
	v_writelane_b32 v83, s15, 12
	v_writelane_b32 v84, s34, 12
	v_writelane_b32 v85, s35, 12
	v_and_b32_e32 v82, 127, v82
	v_sub_u32_e32 v82, 127, v82
	v_and_b32_e32 v83, 127, v83
	v_sub_u32_e32 v83, 127, v83
	v_and_b32_e32 v84, 127, v84
	v_sub_u32_e32 v84, 127, v84
	v_and_b32_e32 v85, 127, v85
	v_sub_u32_e32 v85, 127, v85
	s_add_i32 s19, s18, -1
	v_mov_b32_e32 v236, s19
	v_mov_b32_e32 v237, s18
	v_cmp_eq_u32_e64 s[14:15], 14, v184
	v_cmp_eq_u32_e64 s[34:35], 15, v184
	s_nop 0
	v_cndmask_b32_e64 v82, v82, v236, s[14:15]
	v_cndmask_b32_e64 v82, v82, v237, s[34:35]
	v_cndmask_b32_e64 v83, v83, v236, s[14:15]
	v_cndmask_b32_e64 v83, v83, v237, s[34:35]
	v_cndmask_b32_e64 v84, v84, v236, s[14:15]
	v_cndmask_b32_e64 v84, v84, v237, s[34:35]
	v_cndmask_b32_e64 v85, v85, v236, s[14:15]
	v_cndmask_b32_e64 v85, v85, v237, s[34:35]
	s_and_saveexec_b64 s[42:43], s[6:7]
	ds_write_b32 v196, v82 offset:51264
	ds_write_b32 v196, v83 offset:51328
	ds_write_b32 v196, v84 offset:51392
	ds_write_b32 v196, v85 offset:51456
	s_or_b64 exec, exec, s[42:43]
	s_branch .Ltopk_done_q0

; #define LAS __attribute__((address_space(3)))
; #define CBAR() asm volatile("" ::: "memory")
; __device__ __forceinline__ bf16_t tobf(float x) { return (bf16_t)pk2(x, 0.f); }
; __device__ __forceinline__ void nsa_quad_pre(int bg, int quad, const bf16_t* Q, const bf16_t* KV, const bf16_t* KCMP, const bf16_t* VCMPT, const float* GN, bf16_t* ONSA, ...
;     ...
;         for (int gr = 0; gr < ngr; ++gr) {
;             const bool more = gr + 1 < ngr;
;             qk_scores(KF, qf, sc);
;             if (more) load_k(KF, KP_C(gr + 1));
;             cmp_sm2(sc, gr, t0, bt, inv, Pb, psum, r16, q4);
;             pv_step(VF, oc, Pb, r16, q4);
;             if (more) load_v(VF, VP_C(gr + 1));
;         }
;     }
;     CBAR();
; #pragma unroll
;     for (int tt = 0; tt < 4; ++tt) {
;         const int tok = t0 + tt, cur = tok >> 6;
;         if (cur < 16) { if (lane < 16) selq[tt * 16 + lane] = lane; }
;         else {
;             unsigned k0 = 0u, k1 = 0u;
;             { const int j = lane; if (j >= 1 && j <= cur - 2) { const LAS float* ps = psum + tt * 512 + 4 * j - 1; const float v = ps[0] + ps[1] + ps[2] + ps[3] + ps[4]; k0 = (__builtin_bit_cast(unsigned, v) & ~127u) | (unsigned)(127 - j); } }
;             { const int j = lane + 64; if (j <= cur - 2) { const LAS float* ps = psum + tt * 512 + 4 * j - 1; const float v = ps[0] + ps[1] + ps[2] + ps[3] + ps[4]; k1 = (__builtin_bit_cast(unsigned, v) & ~127u) | (unsigned)(127 - j); } }
;             for (int it = 0; it < 13; ++it) {
;                 unsigned m = k0 > k1 ? k0 : k1;
; #pragma unroll
;                 for (int off = 32; off >= 1; off >>= 1) { const unsigned o = (unsigned)__shfl_xor((int)m, off); m = o > m ? o : m; }
;                 if (k0 == m) k0 = 0u; if (k1 == m) k1 = 0u;
;                 if (lane == 0) selq[tt * 16 + it] = 127 - (int)(m & 127u);
;             }
;             if (lane == 0) { selq[tt * 16 + 13] = 0; selq[tt * 16 + 14] = cur - 1; selq[tt * 16 + 15] = cur; }
;         }
;     }
;     CBAR();
; #pragma unroll
;     for (int tt = 0; tt < 4; ++tt) { const float gc = GN[(size_t)(b * SEQ + t0 + tt) * 48 + (g * 4 + q4) * 3];
;         bf16_t* op = ONSA + (size_t)(b * SEQ + t0 + tt) * 1024 + (g * 4 + q4) * 64 + r16;
; #pragma unroll
;         for (int nt = 0; nt < 4; ++nt) op[nt * 16] = tobf(gc * oc[nt][tt]); }
.Lcmp_tail_q1p2:
	s_waitcnt vmcnt(2) lgkmcnt(0)
	s_barrier
	s_add_i32 s75, s75, 1
	s_cmp_eq_u32 s75, 3
	s_cselect_b32 s75, 0, s75
	s_add_i32 s57, s57, 1
	s_cmp_lt_i32 s57, s74
	s_cbranch_scc1 .Lcmp_top_q1p2
	s_waitcnt lgkmcnt(0)
	s_nop 7
	s_nop 3
	v_and_b32_e32 v232, 15, v184
	v_lshrrev_b32_e32 v233, 4, v184
	v_and_b32_e32 v234, 3, v232
	v_lshrrev_b32_e32 v235, 2, v232
	s_add_i32 s0, s47, s97
	v_add_u32_e32 v253, s0, v234
	s_and_b32 s1, s88, 3
	s_lshl_b32 s1, s1, 2
	v_add_u32_e32 v0, s1, v235
	v_lshlrev_b32_e32 v98, 7, v0
	v_lshl_add_u32 v98, v253, 11, v98
	v_lshl_add_u32 v98, v233, 3, v98
	v_mul_u32_u24_e32 v99, 0xc0, v253
	v_mul_u32_u24_e32 v0, 12, v0
	v_add_u32_e32 v99, v99, v0
	s_add_u32 s72, s30, 0x38310000
	s_addc_u32 s73, s31, 0
	s_add_u32 s14, s30, 0xf900000
	s_addc_u32 s15, s31, 0
	global_load_dword v232, v99, s[72:73]
	s_waitcnt vmcnt(0)
	v_mul_f32_e32 v2, v2, v232
	v_mul_f32_e32 v3, v3, v232
	v_mul_f32_e32 v4, v4, v232
	v_mul_f32_e32 v5, v5, v232
	v_mul_f32_e32 v6, v6, v232
	v_mul_f32_e32 v7, v7, v232
	v_mul_f32_e32 v8, v8, v232
	v_mul_f32_e32 v9, v9, v232
	v_mul_f32_e32 v10, v10, v232
	v_mul_f32_e32 v11, v11, v232
	v_mul_f32_e32 v12, v12, v232
	v_mul_f32_e32 v13, v13, v232
	v_mul_f32_e32 v14, v14, v232
	v_mul_f32_e32 v15, v15, v232
	v_mul_f32_e32 v16, v16, v232
	v_mul_f32_e32 v17, v17, v232
	v_cvt_pk_bf16_f32 v216, v2, v3
	v_cvt_pk_bf16_f32 v217, v4, v5
	v_cvt_pk_bf16_f32 v218, v6, v7
	v_cvt_pk_bf16_f32 v219, v8, v9
	v_cvt_pk_bf16_f32 v220, v10, v11
	v_cvt_pk_bf16_f32 v221, v12, v13
	v_cvt_pk_bf16_f32 v222, v14, v15
	v_cvt_pk_bf16_f32 v223, v16, v17
	global_store_dwordx2 v98, v[216:217], s[14:15] offset:0
	global_store_dwordx2 v98, v[218:219], s[14:15] offset:32
	global_store_dwordx2 v98, v[220:221], s[14:15] offset:64
	global_store_dwordx2 v98, v[222:223], s[14:15] offset:96
	s_waitcnt lgkmcnt(0)
	s_cmp_gt_i32 s18, 15
	s_cbranch_scc0 .Ltopk_small_q1
	s_lshl_b32 s19, s80, 10
	s_add_i32 s19, s19, 56384
	v_lshlrev_b32_e32 v96, 4, v184
	v_add_u32_e32 v96, s19, v96
	v_add_u32_e32 v97, 0xfffffffc, v96
	v_sub_u32_e32 v94, 127, v184
	v_sub_u32_e32 v95, 63, v184
	s_mov_b32 s54, 0xffffff80
	s_add_i32 s21, s18, -2
	v_add_u32_e32 v236, 64, v184
	ds_read_b32 v86, v97 offset:0
	ds_read_b128 v[50:53], v96 offset:0
	ds_read_b32 v87, v97 offset:1024
	ds_read_b128 v[54:57], v96 offset:1024
	ds_read_b32 v88, v97 offset:2048
	ds_read_b128 v[58:61], v96 offset:2048
	ds_read_b32 v89, v97 offset:3072
	ds_read_b128 v[62:65], v96 offset:3072
	s_waitcnt lgkmcnt(6)
	v_add_f32_e32 v86, v86, v50
	v_add_f32_e32 v86, v86, v51
	v_add_f32_e32 v86, v86, v52
	v_add_f32_e32 v86, v86, v53
	v_and_or_b32 v18, v86, s54, v94
	s_waitcnt lgkmcnt(4)
	v_add_f32_e32 v87, v87, v54
	v_add_f32_e32 v87, v87, v55
	v_add_f32_e32 v87, v87, v56
	v_add_f32_e32 v87, v87, v57
	v_and_or_b32 v22, v87, s54, v95
	s_waitcnt lgkmcnt(2)
	v_add_f32_e32 v88, v88, v58
	v_add_f32_e32 v88, v88, v59
	v_add_f32_e32 v88, v88, v60
	v_add_f32_e32 v88, v88, v61
	v_and_or_b32 v19, v88, s54, v94
	s_waitcnt lgkmcnt(0)
	v_add_f32_e32 v89, v89, v62
	v_add_f32_e32 v89, v89, v63
	v_add_f32_e32 v89, v89, v64
	v_add_f32_e32 v89, v89, v65
	v_and_or_b32 v23, v89, s54, v95
	ds_read_b32 v90, v97 offset:4096
	ds_read_b128 v[66:69], v96 offset:4096
	ds_read_b32 v91, v97 offset:5120
	ds_read_b128 v[70:73], v96 offset:5120
	ds_read_b32 v92, v97 offset:6144
	ds_read_b128 v[74:77], v96 offset:6144
	ds_read_b32 v93, v97 offset:7168
	ds_read_b128 v[78:81], v96 offset:7168
	s_waitcnt lgkmcnt(6)
	v_add_f32_e32 v90, v90, v66
	v_add_f32_e32 v90, v90, v67
	v_add_f32_e32 v90, v90, v68
	v_add_f32_e32 v90, v90, v69
	v_and_or_b32 v20, v90, s54, v94
	s_waitcnt lgkmcnt(4)
	v_add_f32_e32 v91, v91, v70
	v_add_f32_e32 v91, v91, v71
	v_add_f32_e32 v91, v91, v72
	v_add_f32_e32 v91, v91, v73
	v_and_or_b32 v24, v91, s54, v95
	s_waitcnt lgkmcnt(2)
	v_add_f32_e32 v92, v92, v74
	v_add_f32_e32 v92, v92, v75
	v_add_f32_e32 v92, v92, v76
	v_add_f32_e32 v92, v92, v77
	v_and_or_b32 v21, v92, s54, v94
	s_waitcnt lgkmcnt(0)
	v_add_f32_e32 v93, v93, v78
	v_add_f32_e32 v93, v93, v79
	v_add_f32_e32 v93, v93, v80
	v_add_f32_e32 v93, v93, v81
	v_and_or_b32 v25, v93, s54, v95
	v_cmp_le_i32_e64 s[14:15], v184, s21
	v_cmp_lt_i32_e64 s[34:35], 0, v184
	s_nop 0
	s_and_b64 s[14:15], s[14:15], s[34:35]
	v_cmp_le_i32_e64 s[34:35], v236, s21
	v_cndmask_b32_e64 v18, 0, v18, s[14:15]
	s_nop 0
	v_cndmask_b32_e64 v22, 0, v22, s[34:35]
	v_mov_b32_e32 v82, 127
	v_cndmask_b32_e64 v19, 0, v19, s[14:15]
	v_cndmask_b32_e64 v23, 0, v23, s[34:35]
	v_mov_b32_e32 v83, 127
	v_cndmask_b32_e64 v20, 0, v20, s[14:15]
	v_cndmask_b32_e64 v24, 0, v24, s[34:35]
	v_mov_b32_e32 v84, 127
	v_cndmask_b32_e64 v21, 0, v21, s[14:15]
	v_cndmask_b32_e64 v25, 0, v25, s[34:35]
	v_mov_b32_e32 v85, 127
	v_max_u32_e32 v26, v18, v22
	v_max_u32_e32 v27, v19, v23
	v_max_u32_e32 v28, v20, v24
	v_max_u32_e32 v29, v21, v25
	v_max_u32_dpp v26, v26, v26 quad_perm:[1,0,3,2] row_mask:0xf bank_mask:0xf
	v_max_u32_dpp v27, v27, v27 quad_perm:[1,0,3,2] row_mask:0xf bank_mask:0xf
	v_max_u32_dpp v28, v28, v28 quad_perm:[1,0,3,2] row_mask:0xf bank_mask:0xf
	v_max_u32_dpp v29, v29, v29 quad_perm:[1,0,3,2] row_mask:0xf bank_mask:0xf
	v_max_u32_dpp v26, v26, v26 quad_perm:[2,3,0,1] row_mask:0xf bank_mask:0xf
	v_max_u32_dpp v27, v27, v27 quad_perm:[2,3,0,1] row_mask:0xf bank_mask:0xf
	v_max_u32_dpp v28, v28, v28 quad_perm:[2,3,0,1] row_mask:0xf bank_mask:0xf
	v_max_u32_dpp v29, v29, v29 quad_perm:[2,3,0,1] row_mask:0xf bank_mask:0xf
	v_max_u32_dpp v26, v26, v26 row_half_mirror row_mask:0xf bank_mask:0xf
	v_max_u32_dpp v27, v27, v27 row_half_mirror row_mask:0xf bank_mask:0xf
	v_max_u32_dpp v28, v28, v28 row_half_mirror row_mask:0xf bank_mask:0xf
; __device__ __forceinline__ void nsa_quad_pre(int bg, int quad, const bf16_t* Q, const bf16_t* KV, const bf16_t* KCMP, const bf16_t* VCMPT, const float* GN, bf16_t* ONSA, ...
;     ...
;             for (int it = 0; it < 13; ++it) {
;                 unsigned m = k0 > k1 ? k0 : k1;
; #pragma unroll
;                 for (int off = 32; off >= 1; off >>= 1) { const unsigned o = (unsigned)__shfl_xor((int)m, off); m = o > m ? o : m; }
;                 if (k0 == m) k0 = 0u; if (k1 == m) k1 = 0u;
;                 if (lane == 0) selq[tt * 16 + it] = 127 - (int)(m & 127u);
	v_max_u32_dpp v29, v29, v29 row_half_mirror row_mask:0xf bank_mask:0xf
	v_max_u32_dpp v26, v26, v26 row_mirror row_mask:0xf bank_mask:0xf
	v_max_u32_dpp v27, v27, v27 row_mirror row_mask:0xf bank_mask:0xf
	v_max_u32_dpp v28, v28, v28 row_mirror row_mask:0xf bank_mask:0xf
	v_max_u32_dpp v29, v29, v29 row_mirror row_mask:0xf bank_mask:0xf
	v_max_u32_dpp v26, v26, v26 row_bcast:15 row_mask:0xa bank_mask:0xf
	v_max_u32_dpp v27, v27, v27 row_bcast:15 row_mask:0xa bank_mask:0xf
	v_max_u32_dpp v28, v28, v28 row_bcast:15 row_mask:0xa bank_mask:0xf
	v_max_u32_dpp v29, v29, v29 row_bcast:15 row_mask:0xa bank_mask:0xf
	v_max_u32_dpp v26, v26, v26 row_bcast:31 row_mask:0xc bank_mask:0xf
	v_max_u32_dpp v27, v27, v27 row_bcast:31 row_mask:0xc bank_mask:0xf
	v_max_u32_dpp v28, v28, v28 row_bcast:31 row_mask:0xc bank_mask:0xf
	v_max_u32_dpp v29, v29, v29 row_bcast:31 row_mask:0xc bank_mask:0xf
	v_readlane_b32 s14, v26, 63
	v_readlane_b32 s15, v27, 63
	v_readlane_b32 s34, v28, 63
	v_readlane_b32 s35, v29, 63
	v_writelane_b32 v82, s14, 0
	v_writelane_b32 v83, s15, 0
	v_writelane_b32 v84, s34, 0
	v_writelane_b32 v85, s35, 0
	v_cmp_ne_u32_e64 s[42:43], s14, v18
	v_cmp_ne_u32_e64 s[66:67], s14, v22
	v_cmp_ne_u32_e64 s[0:1], s15, v19
	v_cmp_ne_u32_e32 vcc, s15, v23
	v_cndmask_b32_e64 v18, 0, v18, s[42:43]
	v_cndmask_b32_e64 v22, 0, v22, s[66:67]
	v_cndmask_b32_e64 v19, 0, v19, s[0:1]
	v_cndmask_b32_e32 v23, 0, v23, vcc
	v_cmp_ne_u32_e64 s[42:43], s34, v20
	v_cmp_ne_u32_e64 s[66:67], s34, v24
	v_cmp_ne_u32_e64 s[0:1], s35, v21
	v_cmp_ne_u32_e32 vcc, s35, v25
	v_cndmask_b32_e64 v20, 0, v20, s[42:43]
	v_cndmask_b32_e64 v24, 0, v24, s[66:67]
	v_cndmask_b32_e64 v21, 0, v21, s[0:1]
	v_cndmask_b32_e32 v25, 0, v25, vcc
	v_max_u32_e32 v26, v18, v22
	v_max_u32_e32 v27, v19, v23
	v_max_u32_e32 v28, v20, v24
	v_max_u32_e32 v29, v21, v25
	v_max_u32_dpp v26, v26, v26 quad_perm:[1,0,3,2] row_mask:0xf bank_mask:0xf
	v_max_u32_dpp v27, v27, v27 quad_perm:[1,0,3,2] row_mask:0xf bank_mask:0xf
	v_max_u32_dpp v28, v28, v28 quad_perm:[1,0,3,2] row_mask:0xf bank_mask:0xf
	v_max_u32_dpp v29, v29, v29 quad_perm:[1,0,3,2] row_mask:0xf bank_mask:0xf
	v_max_u32_dpp v26, v26, v26 quad_perm:[2,3,0,1] row_mask:0xf bank_mask:0xf
	v_max_u32_dpp v27, v27, v27 quad_perm:[2,3,0,1] row_mask:0xf bank_mask:0xf
	v_max_u32_dpp v28, v28, v28 quad_perm:[2,3,0,1] row_mask:0xf bank_mask:0xf
	v_max_u32_dpp v29, v29, v29 quad_perm:[2,3,0,1] row_mask:0xf bank_mask:0xf
	v_max_u32_dpp v26, v26, v26 row_half_mirror row_mask:0xf bank_mask:0xf
	v_max_u32_dpp v27, v27, v27 row_half_mirror row_mask:0xf bank_mask:0xf
	v_max_u32_dpp v28, v28, v28 row_half_mirror row_mask:0xf bank_mask:0xf
	v_max_u32_dpp v29, v29, v29 row_half_mirror row_mask:0xf bank_mask:0xf
	v_max_u32_dpp v26, v26, v26 row_mirror row_mask:0xf bank_mask:0xf
	v_max_u32_dpp v27, v27, v27 row_mirror row_mask:0xf bank_mask:0xf
	v_max_u32_dpp v28, v28, v28 row_mirror row_mask:0xf bank_mask:0xf
	v_max_u32_dpp v29, v29, v29 row_mirror row_mask:0xf bank_mask:0xf
	v_max_u32_dpp v26, v26, v26 row_bcast:15 row_mask:0xa bank_mask:0xf
	v_max_u32_dpp v27, v27, v27 row_bcast:15 row_mask:0xa bank_mask:0xf
	v_max_u32_dpp v28, v28, v28 row_bcast:15 row_mask:0xa bank_mask:0xf
	v_max_u32_dpp v29, v29, v29 row_bcast:15 row_mask:0xa bank_mask:0xf
	v_max_u32_dpp v26, v26, v26 row_bcast:31 row_mask:0xc bank_mask:0xf
	v_max_u32_dpp v27, v27, v27 row_bcast:31 row_mask:0xc bank_mask:0xf
	v_max_u32_dpp v28, v28, v28 row_bcast:31 row_mask:0xc bank_mask:0xf
	v_max_u32_dpp v29, v29, v29 row_bcast:31 row_mask:0xc bank_mask:0xf
	v_readlane_b32 s14, v26, 63
	v_readlane_b32 s15, v27, 63
	v_readlane_b32 s34, v28, 63
	v_readlane_b32 s35, v29, 63
	v_writelane_b32 v82, s14, 1
	v_writelane_b32 v83, s15, 1
	v_writelane_b32 v84, s34, 1
	v_writelane_b32 v85, s35, 1
	v_cmp_ne_u32_e64 s[42:43], s14, v18
	v_cmp_ne_u32_e64 s[66:67], s14, v22
	v_cmp_ne_u32_e64 s[0:1], s15, v19
	v_cmp_ne_u32_e32 vcc, s15, v23
	v_cndmask_b32_e64 v18, 0, v18, s[42:43]
	v_cndmask_b32_e64 v22, 0, v22, s[66:67]
	v_cndmask_b32_e64 v19, 0, v19, s[0:1]
	v_cndmask_b32_e32 v23, 0, v23, vcc
	v_cmp_ne_u32_e64 s[42:43], s34, v20
	v_cmp_ne_u32_e64 s[66:67], s34, v24
	v_cmp_ne_u32_e64 s[0:1], s35, v21
	v_cmp_ne_u32_e32 vcc, s35, v25
	v_cndmask_b32_e64 v20, 0, v20, s[42:43]
	v_cndmask_b32_e64 v24, 0, v24, s[66:67]
	v_cndmask_b32_e64 v21, 0, v21, s[0:1]
	v_cndmask_b32_e32 v25, 0, v25, vcc
	v_max_u32_e32 v26, v18, v22
	v_max_u32_e32 v27, v19, v23
	v_max_u32_e32 v28, v20, v24
	v_max_u32_e32 v29, v21, v25
	v_max_u32_dpp v26, v26, v26 quad_perm:[1,0,3,2] row_mask:0xf bank_mask:0xf
	v_max_u32_dpp v27, v27, v27 quad_perm:[1,0,3,2] row_mask:0xf bank_mask:0xf
	v_max_u32_dpp v28, v28, v28 quad_perm:[1,0,3,2] row_mask:0xf bank_mask:0xf
	v_max_u32_dpp v29, v29, v29 quad_perm:[1,0,3,2] row_mask:0xf bank_mask:0xf
	v_max_u32_dpp v26, v26, v26 quad_perm:[2,3,0,1] row_mask:0xf bank_mask:0xf
	v_max_u32_dpp v27, v27, v27 quad_perm:[2,3,0,1] row_mask:0xf bank_mask:0xf
	v_max_u32_dpp v28, v28, v28 quad_perm:[2,3,0,1] row_mask:0xf bank_mask:0xf
	v_max_u32_dpp v29, v29, v29 quad_perm:[2,3,0,1] row_mask:0xf bank_mask:0xf
	v_max_u32_dpp v26, v26, v26 row_half_mirror row_mask:0xf bank_mask:0xf
	v_max_u32_dpp v27, v27, v27 row_half_mirror row_mask:0xf bank_mask:0xf
	v_max_u32_dpp v28, v28, v28 row_half_mirror row_mask:0xf bank_mask:0xf
	v_max_u32_dpp v29, v29, v29 row_half_mirror row_mask:0xf bank_mask:0xf
	v_max_u32_dpp v26, v26, v26 row_mirror row_mask:0xf bank_mask:0xf
	v_max_u32_dpp v27, v27, v27 row_mirror row_mask:0xf bank_mask:0xf
	v_max_u32_dpp v28, v28, v28 row_mirror row_mask:0xf bank_mask:0xf
	v_max_u32_dpp v29, v29, v29 row_mirror row_mask:0xf bank_mask:0xf
; __device__ __forceinline__ void nsa_quad_pre(int bg, int quad, const bf16_t* Q, const bf16_t* KV, const bf16_t* KCMP, const bf16_t* VCMPT, const float* GN, bf16_t* ONSA, ...
;     ...
;             for (int it = 0; it < 13; ++it) {
;                 unsigned m = k0 > k1 ? k0 : k1;
; #pragma unroll
;                 for (int off = 32; off >= 1; off >>= 1) { const unsigned o = (unsigned)__shfl_xor((int)m, off); m = o > m ? o : m; }
;                 if (k0 == m) k0 = 0u; if (k1 == m) k1 = 0u;
;                 if (lane == 0) selq[tt * 16 + it] = 127 - (int)(m & 127u);
	v_max_u32_dpp v26, v26, v26 row_bcast:15 row_mask:0xa bank_mask:0xf
	v_max_u32_dpp v27, v27, v27 row_bcast:15 row_mask:0xa bank_mask:0xf
	v_max_u32_dpp v28, v28, v28 row_bcast:15 row_mask:0xa bank_mask:0xf
	v_max_u32_dpp v29, v29, v29 row_bcast:15 row_mask:0xa bank_mask:0xf
	v_max_u32_dpp v26, v26, v26 row_bcast:31 row_mask:0xc bank_mask:0xf
	v_max_u32_dpp v27, v27, v27 row_bcast:31 row_mask:0xc bank_mask:0xf
	v_max_u32_dpp v28, v28, v28 row_bcast:31 row_mask:0xc bank_mask:0xf
	v_max_u32_dpp v29, v29, v29 row_bcast:31 row_mask:0xc bank_mask:0xf
	v_readlane_b32 s14, v26, 63
	v_readlane_b32 s15, v27, 63
	v_readlane_b32 s34, v28, 63
	v_readlane_b32 s35, v29, 63
	v_writelane_b32 v82, s14, 2
	v_writelane_b32 v83, s15, 2
	v_writelane_b32 v84, s34, 2
	v_writelane_b32 v85, s35, 2
	v_cmp_ne_u32_e64 s[42:43], s14, v18
	v_cmp_ne_u32_e64 s[66:67], s14, v22
	v_cmp_ne_u32_e64 s[0:1], s15, v19
	v_cmp_ne_u32_e32 vcc, s15, v23
	v_cndmask_b32_e64 v18, 0, v18, s[42:43]
	v_cndmask_b32_e64 v22, 0, v22, s[66:67]
	v_cndmask_b32_e64 v19, 0, v19, s[0:1]
	v_cndmask_b32_e32 v23, 0, v23, vcc
	v_cmp_ne_u32_e64 s[42:43], s34, v20
	v_cmp_ne_u32_e64 s[66:67], s34, v24
	v_cmp_ne_u32_e64 s[0:1], s35, v21
	v_cmp_ne_u32_e32 vcc, s35, v25
	v_cndmask_b32_e64 v20, 0, v20, s[42:43]
	v_cndmask_b32_e64 v24, 0, v24, s[66:67]
	v_cndmask_b32_e64 v21, 0, v21, s[0:1]
	v_cndmask_b32_e32 v25, 0, v25, vcc
	v_max_u32_e32 v26, v18, v22
	v_max_u32_e32 v27, v19, v23
	v_max_u32_e32 v28, v20, v24
	v_max_u32_e32 v29, v21, v25
	v_max_u32_dpp v26, v26, v26 quad_perm:[1,0,3,2] row_mask:0xf bank_mask:0xf
	v_max_u32_dpp v27, v27, v27 quad_perm:[1,0,3,2] row_mask:0xf bank_mask:0xf
	v_max_u32_dpp v28, v28, v28 quad_perm:[1,0,3,2] row_mask:0xf bank_mask:0xf
	v_max_u32_dpp v29, v29, v29 quad_perm:[1,0,3,2] row_mask:0xf bank_mask:0xf
	v_max_u32_dpp v26, v26, v26 quad_perm:[2,3,0,1] row_mask:0xf bank_mask:0xf
	v_max_u32_dpp v27, v27, v27 quad_perm:[2,3,0,1] row_mask:0xf bank_mask:0xf
	v_max_u32_dpp v28, v28, v28 quad_perm:[2,3,0,1] row_mask:0xf bank_mask:0xf
	v_max_u32_dpp v29, v29, v29 quad_perm:[2,3,0,1] row_mask:0xf bank_mask:0xf
	v_max_u32_dpp v26, v26, v26 row_half_mirror row_mask:0xf bank_mask:0xf
	v_max_u32_dpp v27, v27, v27 row_half_mirror row_mask:0xf bank_mask:0xf
	v_max_u32_dpp v28, v28, v28 row_half_mirror row_mask:0xf bank_mask:0xf
	v_max_u32_dpp v29, v29, v29 row_half_mirror row_mask:0xf bank_mask:0xf
	v_max_u32_dpp v26, v26, v26 row_mirror row_mask:0xf bank_mask:0xf
	v_max_u32_dpp v27, v27, v27 row_mirror row_mask:0xf bank_mask:0xf
	v_max_u32_dpp v28, v28, v28 row_mirror row_mask:0xf bank_mask:0xf
	v_max_u32_dpp v29, v29, v29 row_mirror row_mask:0xf bank_mask:0xf
	v_max_u32_dpp v26, v26, v26 row_bcast:15 row_mask:0xa bank_mask:0xf
	v_max_u32_dpp v27, v27, v27 row_bcast:15 row_mask:0xa bank_mask:0xf
	v_max_u32_dpp v28, v28, v28 row_bcast:15 row_mask:0xa bank_mask:0xf
	v_max_u32_dpp v29, v29, v29 row_bcast:15 row_mask:0xa bank_mask:0xf
	v_max_u32_dpp v26, v26, v26 row_bcast:31 row_mask:0xc bank_mask:0xf
	v_max_u32_dpp v27, v27, v27 row_bcast:31 row_mask:0xc bank_mask:0xf
	v_max_u32_dpp v28, v28, v28 row_bcast:31 row_mask:0xc bank_mask:0xf
	v_max_u32_dpp v29, v29, v29 row_bcast:31 row_mask:0xc bank_mask:0xf
	v_readlane_b32 s14, v26, 63
	v_readlane_b32 s15, v27, 63
	v_readlane_b32 s34, v28, 63
	v_readlane_b32 s35, v29, 63
	v_writelane_b32 v82, s14, 3
	v_writelane_b32 v83, s15, 3
	v_writelane_b32 v84, s34, 3
	v_writelane_b32 v85, s35, 3
	v_cmp_ne_u32_e64 s[42:43], s14, v18
	v_cmp_ne_u32_e64 s[66:67], s14, v22
	v_cmp_ne_u32_e64 s[0:1], s15, v19
	v_cmp_ne_u32_e32 vcc, s15, v23
	v_cndmask_b32_e64 v18, 0, v18, s[42:43]
	v_cndmask_b32_e64 v22, 0, v22, s[66:67]
	v_cndmask_b32_e64 v19, 0, v19, s[0:1]
	v_cndmask_b32_e32 v23, 0, v23, vcc
	v_cmp_ne_u32_e64 s[42:43], s34, v20
	v_cmp_ne_u32_e64 s[66:67], s34, v24
	v_cmp_ne_u32_e64 s[0:1], s35, v21
	v_cmp_ne_u32_e32 vcc, s35, v25
	v_cndmask_b32_e64 v20, 0, v20, s[42:43]
	v_cndmask_b32_e64 v24, 0, v24, s[66:67]
	v_cndmask_b32_e64 v21, 0, v21, s[0:1]
	v_cndmask_b32_e32 v25, 0, v25, vcc
	v_max_u32_e32 v26, v18, v22
	v_max_u32_e32 v27, v19, v23
	v_max_u32_e32 v28, v20, v24
	v_max_u32_e32 v29, v21, v25
	v_max_u32_dpp v26, v26, v26 quad_perm:[1,0,3,2] row_mask:0xf bank_mask:0xf
	v_max_u32_dpp v27, v27, v27 quad_perm:[1,0,3,2] row_mask:0xf bank_mask:0xf
	v_max_u32_dpp v28, v28, v28 quad_perm:[1,0,3,2] row_mask:0xf bank_mask:0xf
	v_max_u32_dpp v29, v29, v29 quad_perm:[1,0,3,2] row_mask:0xf bank_mask:0xf
	v_max_u32_dpp v26, v26, v26 quad_perm:[2,3,0,1] row_mask:0xf bank_mask:0xf
	v_max_u32_dpp v27, v27, v27 quad_perm:[2,3,0,1] row_mask:0xf bank_mask:0xf
	v_max_u32_dpp v28, v28, v28 quad_perm:[2,3,0,1] row_mask:0xf bank_mask:0xf
	v_max_u32_dpp v29, v29, v29 quad_perm:[2,3,0,1] row_mask:0xf bank_mask:0xf
	v_max_u32_dpp v26, v26, v26 row_half_mirror row_mask:0xf bank_mask:0xf
	v_max_u32_dpp v27, v27, v27 row_half_mirror row_mask:0xf bank_mask:0xf
	v_max_u32_dpp v28, v28, v28 row_half_mirror row_mask:0xf bank_mask:0xf
	v_max_u32_dpp v29, v29, v29 row_half_mirror row_mask:0xf bank_mask:0xf
	v_max_u32_dpp v26, v26, v26 row_mirror row_mask:0xf bank_mask:0xf
	v_max_u32_dpp v27, v27, v27 row_mirror row_mask:0xf bank_mask:0xf
	v_max_u32_dpp v28, v28, v28 row_mirror row_mask:0xf bank_mask:0xf
	v_max_u32_dpp v29, v29, v29 row_mirror row_mask:0xf bank_mask:0xf
	v_max_u32_dpp v26, v26, v26 row_bcast:15 row_mask:0xa bank_mask:0xf
	v_max_u32_dpp v27, v27, v27 row_bcast:15 row_mask:0xa bank_mask:0xf
	v_max_u32_dpp v28, v28, v28 row_bcast:15 row_mask:0xa bank_mask:0xf
	v_max_u32_dpp v29, v29, v29 row_bcast:15 row_mask:0xa bank_mask:0xf
	v_max_u32_dpp v26, v26, v26 row_bcast:31 row_mask:0xc bank_mask:0xf
; __device__ __forceinline__ void nsa_quad_pre(int bg, int quad, const bf16_t* Q, const bf16_t* KV, const bf16_t* KCMP, const bf16_t* VCMPT, const float* GN, bf16_t* ONSA, ...
;     ...
;             for (int it = 0; it < 13; ++it) {
;                 unsigned m = k0 > k1 ? k0 : k1;
; #pragma unroll
;                 for (int off = 32; off >= 1; off >>= 1) { const unsigned o = (unsigned)__shfl_xor((int)m, off); m = o > m ? o : m; }
;                 if (k0 == m) k0 = 0u; if (k1 == m) k1 = 0u;
;                 if (lane == 0) selq[tt * 16 + it] = 127 - (int)(m & 127u);
	v_max_u32_dpp v27, v27, v27 row_bcast:31 row_mask:0xc bank_mask:0xf
	v_max_u32_dpp v28, v28, v28 row_bcast:31 row_mask:0xc bank_mask:0xf
	v_max_u32_dpp v29, v29, v29 row_bcast:31 row_mask:0xc bank_mask:0xf
	v_readlane_b32 s14, v26, 63
	v_readlane_b32 s15, v27, 63
	v_readlane_b32 s34, v28, 63
	v_readlane_b32 s35, v29, 63
	v_writelane_b32 v82, s14, 4
	v_writelane_b32 v83, s15, 4
	v_writelane_b32 v84, s34, 4
	v_writelane_b32 v85, s35, 4
	v_cmp_ne_u32_e64 s[42:43], s14, v18
	v_cmp_ne_u32_e64 s[66:67], s14, v22
	v_cmp_ne_u32_e64 s[0:1], s15, v19
	v_cmp_ne_u32_e32 vcc, s15, v23
	v_cndmask_b32_e64 v18, 0, v18, s[42:43]
	v_cndmask_b32_e64 v22, 0, v22, s[66:67]
	v_cndmask_b32_e64 v19, 0, v19, s[0:1]
	v_cndmask_b32_e32 v23, 0, v23, vcc
	v_cmp_ne_u32_e64 s[42:43], s34, v20
	v_cmp_ne_u32_e64 s[66:67], s34, v24
	v_cmp_ne_u32_e64 s[0:1], s35, v21
	v_cmp_ne_u32_e32 vcc, s35, v25
	v_cndmask_b32_e64 v20, 0, v20, s[42:43]
	v_cndmask_b32_e64 v24, 0, v24, s[66:67]
	v_cndmask_b32_e64 v21, 0, v21, s[0:1]
	v_cndmask_b32_e32 v25, 0, v25, vcc
	v_max_u32_e32 v26, v18, v22
	v_max_u32_e32 v27, v19, v23
	v_max_u32_e32 v28, v20, v24
	v_max_u32_e32 v29, v21, v25
	v_max_u32_dpp v26, v26, v26 quad_perm:[1,0,3,2] row_mask:0xf bank_mask:0xf
	v_max_u32_dpp v27, v27, v27 quad_perm:[1,0,3,2] row_mask:0xf bank_mask:0xf
	v_max_u32_dpp v28, v28, v28 quad_perm:[1,0,3,2] row_mask:0xf bank_mask:0xf
	v_max_u32_dpp v29, v29, v29 quad_perm:[1,0,3,2] row_mask:0xf bank_mask:0xf
	v_max_u32_dpp v26, v26, v26 quad_perm:[2,3,0,1] row_mask:0xf bank_mask:0xf
	v_max_u32_dpp v27, v27, v27 quad_perm:[2,3,0,1] row_mask:0xf bank_mask:0xf
	v_max_u32_dpp v28, v28, v28 quad_perm:[2,3,0,1] row_mask:0xf bank_mask:0xf
	v_max_u32_dpp v29, v29, v29 quad_perm:[2,3,0,1] row_mask:0xf bank_mask:0xf
	v_max_u32_dpp v26, v26, v26 row_half_mirror row_mask:0xf bank_mask:0xf
	v_max_u32_dpp v27, v27, v27 row_half_mirror row_mask:0xf bank_mask:0xf
	v_max_u32_dpp v28, v28, v28 row_half_mirror row_mask:0xf bank_mask:0xf
	v_max_u32_dpp v29, v29, v29 row_half_mirror row_mask:0xf bank_mask:0xf
	v_max_u32_dpp v26, v26, v26 row_mirror row_mask:0xf bank_mask:0xf
	v_max_u32_dpp v27, v27, v27 row_mirror row_mask:0xf bank_mask:0xf
	v_max_u32_dpp v28, v28, v28 row_mirror row_mask:0xf bank_mask:0xf
	v_max_u32_dpp v29, v29, v29 row_mirror row_mask:0xf bank_mask:0xf
	v_max_u32_dpp v26, v26, v26 row_bcast:15 row_mask:0xa bank_mask:0xf
	v_max_u32_dpp v27, v27, v27 row_bcast:15 row_mask:0xa bank_mask:0xf
	v_max_u32_dpp v28, v28, v28 row_bcast:15 row_mask:0xa bank_mask:0xf
	v_max_u32_dpp v29, v29, v29 row_bcast:15 row_mask:0xa bank_mask:0xf
	v_max_u32_dpp v26, v26, v26 row_bcast:31 row_mask:0xc bank_mask:0xf
	v_max_u32_dpp v27, v27, v27 row_bcast:31 row_mask:0xc bank_mask:0xf
	v_max_u32_dpp v28, v28, v28 row_bcast:31 row_mask:0xc bank_mask:0xf
	v_max_u32_dpp v29, v29, v29 row_bcast:31 row_mask:0xc bank_mask:0xf
	v_readlane_b32 s14, v26, 63
	v_readlane_b32 s15, v27, 63
	v_readlane_b32 s34, v28, 63
	v_readlane_b32 s35, v29, 63
	v_writelane_b32 v82, s14, 5
	v_writelane_b32 v83, s15, 5
	v_writelane_b32 v84, s34, 5
	v_writelane_b32 v85, s35, 5
	v_cmp_ne_u32_e64 s[42:43], s14, v18
	v_cmp_ne_u32_e64 s[66:67], s14, v22
	v_cmp_ne_u32_e64 s[0:1], s15, v19
	v_cmp_ne_u32_e32 vcc, s15, v23
	v_cndmask_b32_e64 v18, 0, v18, s[42:43]
	v_cndmask_b32_e64 v22, 0, v22, s[66:67]
	v_cndmask_b32_e64 v19, 0, v19, s[0:1]
	v_cndmask_b32_e32 v23, 0, v23, vcc
	v_cmp_ne_u32_e64 s[42:43], s34, v20
	v_cmp_ne_u32_e64 s[66:67], s34, v24
	v_cmp_ne_u32_e64 s[0:1], s35, v21
	v_cmp_ne_u32_e32 vcc, s35, v25
	v_cndmask_b32_e64 v20, 0, v20, s[42:43]
	v_cndmask_b32_e64 v24, 0, v24, s[66:67]
	v_cndmask_b32_e64 v21, 0, v21, s[0:1]
	v_cndmask_b32_e32 v25, 0, v25, vcc
	v_max_u32_e32 v26, v18, v22
	v_max_u32_e32 v27, v19, v23
	v_max_u32_e32 v28, v20, v24
	v_max_u32_e32 v29, v21, v25
	v_max_u32_dpp v26, v26, v26 quad_perm:[1,0,3,2] row_mask:0xf bank_mask:0xf
	v_max_u32_dpp v27, v27, v27 quad_perm:[1,0,3,2] row_mask:0xf bank_mask:0xf
	v_max_u32_dpp v28, v28, v28 quad_perm:[1,0,3,2] row_mask:0xf bank_mask:0xf
	v_max_u32_dpp v29, v29, v29 quad_perm:[1,0,3,2] row_mask:0xf bank_mask:0xf
	v_max_u32_dpp v26, v26, v26 quad_perm:[2,3,0,1] row_mask:0xf bank_mask:0xf
	v_max_u32_dpp v27, v27, v27 quad_perm:[2,3,0,1] row_mask:0xf bank_mask:0xf
	v_max_u32_dpp v28, v28, v28 quad_perm:[2,3,0,1] row_mask:0xf bank_mask:0xf
	v_max_u32_dpp v29, v29, v29 quad_perm:[2,3,0,1] row_mask:0xf bank_mask:0xf
	v_max_u32_dpp v26, v26, v26 row_half_mirror row_mask:0xf bank_mask:0xf
	v_max_u32_dpp v27, v27, v27 row_half_mirror row_mask:0xf bank_mask:0xf
	v_max_u32_dpp v28, v28, v28 row_half_mirror row_mask:0xf bank_mask:0xf
	v_max_u32_dpp v29, v29, v29 row_half_mirror row_mask:0xf bank_mask:0xf
	v_max_u32_dpp v26, v26, v26 row_mirror row_mask:0xf bank_mask:0xf
	v_max_u32_dpp v27, v27, v27 row_mirror row_mask:0xf bank_mask:0xf
	v_max_u32_dpp v28, v28, v28 row_mirror row_mask:0xf bank_mask:0xf
	v_max_u32_dpp v29, v29, v29 row_mirror row_mask:0xf bank_mask:0xf
	v_max_u32_dpp v26, v26, v26 row_bcast:15 row_mask:0xa bank_mask:0xf
	v_max_u32_dpp v27, v27, v27 row_bcast:15 row_mask:0xa bank_mask:0xf
	v_max_u32_dpp v28, v28, v28 row_bcast:15 row_mask:0xa bank_mask:0xf
	v_max_u32_dpp v29, v29, v29 row_bcast:15 row_mask:0xa bank_mask:0xf
	v_max_u32_dpp v26, v26, v26 row_bcast:31 row_mask:0xc bank_mask:0xf
	v_max_u32_dpp v27, v27, v27 row_bcast:31 row_mask:0xc bank_mask:0xf
	v_max_u32_dpp v28, v28, v28 row_bcast:31 row_mask:0xc bank_mask:0xf
	v_max_u32_dpp v29, v29, v29 row_bcast:31 row_mask:0xc bank_mask:0xf
	v_readlane_b32 s14, v26, 63
	v_readlane_b32 s15, v27, 63
	v_readlane_b32 s34, v28, 63
	v_readlane_b32 s35, v29, 63
; __device__ __forceinline__ void nsa_quad_pre(int bg, int quad, const bf16_t* Q, const bf16_t* KV, const bf16_t* KCMP, const bf16_t* VCMPT, const float* GN, bf16_t* ONSA, ...
;     ...
;             for (int it = 0; it < 13; ++it) {
;                 unsigned m = k0 > k1 ? k0 : k1;
; #pragma unroll
;                 for (int off = 32; off >= 1; off >>= 1) { const unsigned o = (unsigned)__shfl_xor((int)m, off); m = o > m ? o : m; }
;                 if (k0 == m) k0 = 0u; if (k1 == m) k1 = 0u;
;                 if (lane == 0) selq[tt * 16 + it] = 127 - (int)(m & 127u);
	v_writelane_b32 v82, s14, 6
	v_writelane_b32 v83, s15, 6
	v_writelane_b32 v84, s34, 6
	v_writelane_b32 v85, s35, 6
	v_cmp_ne_u32_e64 s[42:43], s14, v18
	v_cmp_ne_u32_e64 s[66:67], s14, v22
	v_cmp_ne_u32_e64 s[0:1], s15, v19
	v_cmp_ne_u32_e32 vcc, s15, v23
	v_cndmask_b32_e64 v18, 0, v18, s[42:43]
	v_cndmask_b32_e64 v22, 0, v22, s[66:67]
	v_cndmask_b32_e64 v19, 0, v19, s[0:1]
	v_cndmask_b32_e32 v23, 0, v23, vcc
	v_cmp_ne_u32_e64 s[42:43], s34, v20
	v_cmp_ne_u32_e64 s[66:67], s34, v24
	v_cmp_ne_u32_e64 s[0:1], s35, v21
	v_cmp_ne_u32_e32 vcc, s35, v25
	v_cndmask_b32_e64 v20, 0, v20, s[42:43]
	v_cndmask_b32_e64 v24, 0, v24, s[66:67]
	v_cndmask_b32_e64 v21, 0, v21, s[0:1]
	v_cndmask_b32_e32 v25, 0, v25, vcc
	v_max_u32_e32 v26, v18, v22
	v_max_u32_e32 v27, v19, v23
	v_max_u32_e32 v28, v20, v24
	v_max_u32_e32 v29, v21, v25
	v_max_u32_dpp v26, v26, v26 quad_perm:[1,0,3,2] row_mask:0xf bank_mask:0xf
	v_max_u32_dpp v27, v27, v27 quad_perm:[1,0,3,2] row_mask:0xf bank_mask:0xf
	v_max_u32_dpp v28, v28, v28 quad_perm:[1,0,3,2] row_mask:0xf bank_mask:0xf
	v_max_u32_dpp v29, v29, v29 quad_perm:[1,0,3,2] row_mask:0xf bank_mask:0xf
	v_max_u32_dpp v26, v26, v26 quad_perm:[2,3,0,1] row_mask:0xf bank_mask:0xf
	v_max_u32_dpp v27, v27, v27 quad_perm:[2,3,0,1] row_mask:0xf bank_mask:0xf
	v_max_u32_dpp v28, v28, v28 quad_perm:[2,3,0,1] row_mask:0xf bank_mask:0xf
	v_max_u32_dpp v29, v29, v29 quad_perm:[2,3,0,1] row_mask:0xf bank_mask:0xf
	v_max_u32_dpp v26, v26, v26 row_half_mirror row_mask:0xf bank_mask:0xf
	v_max_u32_dpp v27, v27, v27 row_half_mirror row_mask:0xf bank_mask:0xf
	v_max_u32_dpp v28, v28, v28 row_half_mirror row_mask:0xf bank_mask:0xf
	v_max_u32_dpp v29, v29, v29 row_half_mirror row_mask:0xf bank_mask:0xf
	v_max_u32_dpp v26, v26, v26 row_mirror row_mask:0xf bank_mask:0xf
	v_max_u32_dpp v27, v27, v27 row_mirror row_mask:0xf bank_mask:0xf
	v_max_u32_dpp v28, v28, v28 row_mirror row_mask:0xf bank_mask:0xf
	v_max_u32_dpp v29, v29, v29 row_mirror row_mask:0xf bank_mask:0xf
	v_max_u32_dpp v26, v26, v26 row_bcast:15 row_mask:0xa bank_mask:0xf
	v_max_u32_dpp v27, v27, v27 row_bcast:15 row_mask:0xa bank_mask:0xf
	v_max_u32_dpp v28, v28, v28 row_bcast:15 row_mask:0xa bank_mask:0xf
	v_max_u32_dpp v29, v29, v29 row_bcast:15 row_mask:0xa bank_mask:0xf
	v_max_u32_dpp v26, v26, v26 row_bcast:31 row_mask:0xc bank_mask:0xf
	v_max_u32_dpp v27, v27, v27 row_bcast:31 row_mask:0xc bank_mask:0xf
	v_max_u32_dpp v28, v28, v28 row_bcast:31 row_mask:0xc bank_mask:0xf
	v_max_u32_dpp v29, v29, v29 row_bcast:31 row_mask:0xc bank_mask:0xf
	v_readlane_b32 s14, v26, 63
	v_readlane_b32 s15, v27, 63
	v_readlane_b32 s34, v28, 63
	v_readlane_b32 s35, v29, 63
	v_writelane_b32 v82, s14, 7
	v_writelane_b32 v83, s15, 7
	v_writelane_b32 v84, s34, 7
	v_writelane_b32 v85, s35, 7
	v_cmp_ne_u32_e64 s[42:43], s14, v18
	v_cmp_ne_u32_e64 s[66:67], s14, v22
	v_cmp_ne_u32_e64 s[0:1], s15, v19
	v_cmp_ne_u32_e32 vcc, s15, v23
	v_cndmask_b32_e64 v18, 0, v18, s[42:43]
	v_cndmask_b32_e64 v22, 0, v22, s[66:67]
	v_cndmask_b32_e64 v19, 0, v19, s[0:1]
	v_cndmask_b32_e32 v23, 0, v23, vcc
	v_cmp_ne_u32_e64 s[42:43], s34, v20
	v_cmp_ne_u32_e64 s[66:67], s34, v24
	v_cmp_ne_u32_e64 s[0:1], s35, v21
	v_cmp_ne_u32_e32 vcc, s35, v25
	v_cndmask_b32_e64 v20, 0, v20, s[42:43]
	v_cndmask_b32_e64 v24, 0, v24, s[66:67]
	v_cndmask_b32_e64 v21, 0, v21, s[0:1]
	v_cndmask_b32_e32 v25, 0, v25, vcc
	v_max_u32_e32 v26, v18, v22
	v_max_u32_e32 v27, v19, v23
	v_max_u32_e32 v28, v20, v24
	v_max_u32_e32 v29, v21, v25
	v_max_u32_dpp v26, v26, v26 quad_perm:[1,0,3,2] row_mask:0xf bank_mask:0xf
	v_max_u32_dpp v27, v27, v27 quad_perm:[1,0,3,2] row_mask:0xf bank_mask:0xf
	v_max_u32_dpp v28, v28, v28 quad_perm:[1,0,3,2] row_mask:0xf bank_mask:0xf
	v_max_u32_dpp v29, v29, v29 quad_perm:[1,0,3,2] row_mask:0xf bank_mask:0xf
	v_max_u32_dpp v26, v26, v26 quad_perm:[2,3,0,1] row_mask:0xf bank_mask:0xf
	v_max_u32_dpp v27, v27, v27 quad_perm:[2,3,0,1] row_mask:0xf bank_mask:0xf
	v_max_u32_dpp v28, v28, v28 quad_perm:[2,3,0,1] row_mask:0xf bank_mask:0xf
	v_max_u32_dpp v29, v29, v29 quad_perm:[2,3,0,1] row_mask:0xf bank_mask:0xf
	v_max_u32_dpp v26, v26, v26 row_half_mirror row_mask:0xf bank_mask:0xf
	v_max_u32_dpp v27, v27, v27 row_half_mirror row_mask:0xf bank_mask:0xf
	v_max_u32_dpp v28, v28, v28 row_half_mirror row_mask:0xf bank_mask:0xf
	v_max_u32_dpp v29, v29, v29 row_half_mirror row_mask:0xf bank_mask:0xf
	v_max_u32_dpp v26, v26, v26 row_mirror row_mask:0xf bank_mask:0xf
	v_max_u32_dpp v27, v27, v27 row_mirror row_mask:0xf bank_mask:0xf
	v_max_u32_dpp v28, v28, v28 row_mirror row_mask:0xf bank_mask:0xf
	v_max_u32_dpp v29, v29, v29 row_mirror row_mask:0xf bank_mask:0xf
	v_max_u32_dpp v26, v26, v26 row_bcast:15 row_mask:0xa bank_mask:0xf
	v_max_u32_dpp v27, v27, v27 row_bcast:15 row_mask:0xa bank_mask:0xf
	v_max_u32_dpp v28, v28, v28 row_bcast:15 row_mask:0xa bank_mask:0xf
	v_max_u32_dpp v29, v29, v29 row_bcast:15 row_mask:0xa bank_mask:0xf
	v_max_u32_dpp v26, v26, v26 row_bcast:31 row_mask:0xc bank_mask:0xf
	v_max_u32_dpp v27, v27, v27 row_bcast:31 row_mask:0xc bank_mask:0xf
	v_max_u32_dpp v28, v28, v28 row_bcast:31 row_mask:0xc bank_mask:0xf
	v_max_u32_dpp v29, v29, v29 row_bcast:31 row_mask:0xc bank_mask:0xf
	v_readlane_b32 s14, v26, 63
	v_readlane_b32 s15, v27, 63
	v_readlane_b32 s34, v28, 63
	v_readlane_b32 s35, v29, 63
	v_writelane_b32 v82, s14, 8
	v_writelane_b32 v83, s15, 8
	v_writelane_b32 v84, s34, 8
	v_writelane_b32 v85, s35, 8
	v_cmp_ne_u32_e64 s[42:43], s14, v18
	v_cmp_ne_u32_e64 s[66:67], s14, v22
	v_cmp_ne_u32_e64 s[0:1], s15, v19
	v_cmp_ne_u32_e32 vcc, s15, v23
	v_cndmask_b32_e64 v18, 0, v18, s[42:43]
	v_cndmask_b32_e64 v22, 0, v22, s[66:67]
; __device__ __forceinline__ void nsa_quad_pre(int bg, int quad, const bf16_t* Q, const bf16_t* KV, const bf16_t* KCMP, const bf16_t* VCMPT, const float* GN, bf16_t* ONSA, ...
;     ...
;             for (int it = 0; it < 13; ++it) {
;                 unsigned m = k0 > k1 ? k0 : k1;
; #pragma unroll
;                 for (int off = 32; off >= 1; off >>= 1) { const unsigned o = (unsigned)__shfl_xor((int)m, off); m = o > m ? o : m; }
;                 if (k0 == m) k0 = 0u; if (k1 == m) k1 = 0u;
;                 if (lane == 0) selq[tt * 16 + it] = 127 - (int)(m & 127u);
	v_cndmask_b32_e64 v19, 0, v19, s[0:1]
	v_cndmask_b32_e32 v23, 0, v23, vcc
	v_cmp_ne_u32_e64 s[42:43], s34, v20
	v_cmp_ne_u32_e64 s[66:67], s34, v24
	v_cmp_ne_u32_e64 s[0:1], s35, v21
	v_cmp_ne_u32_e32 vcc, s35, v25
	v_cndmask_b32_e64 v20, 0, v20, s[42:43]
	v_cndmask_b32_e64 v24, 0, v24, s[66:67]
	v_cndmask_b32_e64 v21, 0, v21, s[0:1]
	v_cndmask_b32_e32 v25, 0, v25, vcc
	v_max_u32_e32 v26, v18, v22
	v_max_u32_e32 v27, v19, v23
	v_max_u32_e32 v28, v20, v24
	v_max_u32_e32 v29, v21, v25
	v_max_u32_dpp v26, v26, v26 quad_perm:[1,0,3,2] row_mask:0xf bank_mask:0xf
	v_max_u32_dpp v27, v27, v27 quad_perm:[1,0,3,2] row_mask:0xf bank_mask:0xf
	v_max_u32_dpp v28, v28, v28 quad_perm:[1,0,3,2] row_mask:0xf bank_mask:0xf
	v_max_u32_dpp v29, v29, v29 quad_perm:[1,0,3,2] row_mask:0xf bank_mask:0xf
	v_max_u32_dpp v26, v26, v26 quad_perm:[2,3,0,1] row_mask:0xf bank_mask:0xf
	v_max_u32_dpp v27, v27, v27 quad_perm:[2,3,0,1] row_mask:0xf bank_mask:0xf
	v_max_u32_dpp v28, v28, v28 quad_perm:[2,3,0,1] row_mask:0xf bank_mask:0xf
	v_max_u32_dpp v29, v29, v29 quad_perm:[2,3,0,1] row_mask:0xf bank_mask:0xf
	v_max_u32_dpp v26, v26, v26 row_half_mirror row_mask:0xf bank_mask:0xf
	v_max_u32_dpp v27, v27, v27 row_half_mirror row_mask:0xf bank_mask:0xf
	v_max_u32_dpp v28, v28, v28 row_half_mirror row_mask:0xf bank_mask:0xf
	v_max_u32_dpp v29, v29, v29 row_half_mirror row_mask:0xf bank_mask:0xf
	v_max_u32_dpp v26, v26, v26 row_mirror row_mask:0xf bank_mask:0xf
	v_max_u32_dpp v27, v27, v27 row_mirror row_mask:0xf bank_mask:0xf
	v_max_u32_dpp v28, v28, v28 row_mirror row_mask:0xf bank_mask:0xf
	v_max_u32_dpp v29, v29, v29 row_mirror row_mask:0xf bank_mask:0xf
	v_max_u32_dpp v26, v26, v26 row_bcast:15 row_mask:0xa bank_mask:0xf
	v_max_u32_dpp v27, v27, v27 row_bcast:15 row_mask:0xa bank_mask:0xf
	v_max_u32_dpp v28, v28, v28 row_bcast:15 row_mask:0xa bank_mask:0xf
	v_max_u32_dpp v29, v29, v29 row_bcast:15 row_mask:0xa bank_mask:0xf
	v_max_u32_dpp v26, v26, v26 row_bcast:31 row_mask:0xc bank_mask:0xf
	v_max_u32_dpp v27, v27, v27 row_bcast:31 row_mask:0xc bank_mask:0xf
	v_max_u32_dpp v28, v28, v28 row_bcast:31 row_mask:0xc bank_mask:0xf
	v_max_u32_dpp v29, v29, v29 row_bcast:31 row_mask:0xc bank_mask:0xf
	v_readlane_b32 s14, v26, 63
	v_readlane_b32 s15, v27, 63
	v_readlane_b32 s34, v28, 63
	v_readlane_b32 s35, v29, 63
	v_writelane_b32 v82, s14, 9
	v_writelane_b32 v83, s15, 9
	v_writelane_b32 v84, s34, 9
	v_writelane_b32 v85, s35, 9
	v_cmp_ne_u32_e64 s[42:43], s14, v18
	v_cmp_ne_u32_e64 s[66:67], s14, v22
	v_cmp_ne_u32_e64 s[0:1], s15, v19
	v_cmp_ne_u32_e32 vcc, s15, v23
	v_cndmask_b32_e64 v18, 0, v18, s[42:43]
	v_cndmask_b32_e64 v22, 0, v22, s[66:67]
	v_cndmask_b32_e64 v19, 0, v19, s[0:1]
	v_cndmask_b32_e32 v23, 0, v23, vcc
	v_cmp_ne_u32_e64 s[42:43], s34, v20
	v_cmp_ne_u32_e64 s[66:67], s34, v24
	v_cmp_ne_u32_e64 s[0:1], s35, v21
	v_cmp_ne_u32_e32 vcc, s35, v25
	v_cndmask_b32_e64 v20, 0, v20, s[42:43]
	v_cndmask_b32_e64 v24, 0, v24, s[66:67]
	v_cndmask_b32_e64 v21, 0, v21, s[0:1]
	v_cndmask_b32_e32 v25, 0, v25, vcc
	v_max_u32_e32 v26, v18, v22
	v_max_u32_e32 v27, v19, v23
	v_max_u32_e32 v28, v20, v24
	v_max_u32_e32 v29, v21, v25
	v_max_u32_dpp v26, v26, v26 quad_perm:[1,0,3,2] row_mask:0xf bank_mask:0xf
	v_max_u32_dpp v27, v27, v27 quad_perm:[1,0,3,2] row_mask:0xf bank_mask:0xf
	v_max_u32_dpp v28, v28, v28 quad_perm:[1,0,3,2] row_mask:0xf bank_mask:0xf
	v_max_u32_dpp v29, v29, v29 quad_perm:[1,0,3,2] row_mask:0xf bank_mask:0xf
	v_max_u32_dpp v26, v26, v26 quad_perm:[2,3,0,1] row_mask:0xf bank_mask:0xf
	v_max_u32_dpp v27, v27, v27 quad_perm:[2,3,0,1] row_mask:0xf bank_mask:0xf
	v_max_u32_dpp v28, v28, v28 quad_perm:[2,3,0,1] row_mask:0xf bank_mask:0xf
	v_max_u32_dpp v29, v29, v29 quad_perm:[2,3,0,1] row_mask:0xf bank_mask:0xf
	v_max_u32_dpp v26, v26, v26 row_half_mirror row_mask:0xf bank_mask:0xf
	v_max_u32_dpp v27, v27, v27 row_half_mirror row_mask:0xf bank_mask:0xf
	v_max_u32_dpp v28, v28, v28 row_half_mirror row_mask:0xf bank_mask:0xf
	v_max_u32_dpp v29, v29, v29 row_half_mirror row_mask:0xf bank_mask:0xf
	v_max_u32_dpp v26, v26, v26 row_mirror row_mask:0xf bank_mask:0xf
	v_max_u32_dpp v27, v27, v27 row_mirror row_mask:0xf bank_mask:0xf
	v_max_u32_dpp v28, v28, v28 row_mirror row_mask:0xf bank_mask:0xf
	v_max_u32_dpp v29, v29, v29 row_mirror row_mask:0xf bank_mask:0xf
	v_max_u32_dpp v26, v26, v26 row_bcast:15 row_mask:0xa bank_mask:0xf
	v_max_u32_dpp v27, v27, v27 row_bcast:15 row_mask:0xa bank_mask:0xf
	v_max_u32_dpp v28, v28, v28 row_bcast:15 row_mask:0xa bank_mask:0xf
	v_max_u32_dpp v29, v29, v29 row_bcast:15 row_mask:0xa bank_mask:0xf
	v_max_u32_dpp v26, v26, v26 row_bcast:31 row_mask:0xc bank_mask:0xf
	v_max_u32_dpp v27, v27, v27 row_bcast:31 row_mask:0xc bank_mask:0xf
	v_max_u32_dpp v28, v28, v28 row_bcast:31 row_mask:0xc bank_mask:0xf
	v_max_u32_dpp v29, v29, v29 row_bcast:31 row_mask:0xc bank_mask:0xf
	v_readlane_b32 s14, v26, 63
	v_readlane_b32 s15, v27, 63
	v_readlane_b32 s34, v28, 63
	v_readlane_b32 s35, v29, 63
	v_writelane_b32 v82, s14, 10
	v_writelane_b32 v83, s15, 10
	v_writelane_b32 v84, s34, 10
	v_writelane_b32 v85, s35, 10
	v_cmp_ne_u32_e64 s[42:43], s14, v18
	v_cmp_ne_u32_e64 s[66:67], s14, v22
	v_cmp_ne_u32_e64 s[0:1], s15, v19
	v_cmp_ne_u32_e32 vcc, s15, v23
	v_cndmask_b32_e64 v18, 0, v18, s[42:43]
	v_cndmask_b32_e64 v22, 0, v22, s[66:67]
	v_cndmask_b32_e64 v19, 0, v19, s[0:1]
	v_cndmask_b32_e32 v23, 0, v23, vcc
	v_cmp_ne_u32_e64 s[42:43], s34, v20
	v_cmp_ne_u32_e64 s[66:67], s34, v24
	v_cmp_ne_u32_e64 s[0:1], s35, v21
	v_cmp_ne_u32_e32 vcc, s35, v25
	v_cndmask_b32_e64 v20, 0, v20, s[42:43]
	v_cndmask_b32_e64 v24, 0, v24, s[66:67]
; __device__ __forceinline__ void nsa_quad_pre(int bg, int quad, const bf16_t* Q, const bf16_t* KV, const bf16_t* KCMP, const bf16_t* VCMPT, const float* GN, bf16_t* ONSA, ...
;     ...
;             for (int it = 0; it < 13; ++it) {
;                 unsigned m = k0 > k1 ? k0 : k1;
; #pragma unroll
;                 for (int off = 32; off >= 1; off >>= 1) { const unsigned o = (unsigned)__shfl_xor((int)m, off); m = o > m ? o : m; }
;                 if (k0 == m) k0 = 0u; if (k1 == m) k1 = 0u;
;                 if (lane == 0) selq[tt * 16 + it] = 127 - (int)(m & 127u);
;             }
;             if (lane == 0) { selq[tt * 16 + 13] = 0; selq[tt * 16 + 14] = cur - 1; selq[tt * 16 + 15] = cur; }
	v_cndmask_b32_e64 v21, 0, v21, s[0:1]
	v_cndmask_b32_e32 v25, 0, v25, vcc
	v_max_u32_e32 v26, v18, v22
	v_max_u32_e32 v27, v19, v23
	v_max_u32_e32 v28, v20, v24
	v_max_u32_e32 v29, v21, v25
	v_max_u32_dpp v26, v26, v26 quad_perm:[1,0,3,2] row_mask:0xf bank_mask:0xf
	v_max_u32_dpp v27, v27, v27 quad_perm:[1,0,3,2] row_mask:0xf bank_mask:0xf
	v_max_u32_dpp v28, v28, v28 quad_perm:[1,0,3,2] row_mask:0xf bank_mask:0xf
	v_max_u32_dpp v29, v29, v29 quad_perm:[1,0,3,2] row_mask:0xf bank_mask:0xf
	v_max_u32_dpp v26, v26, v26 quad_perm:[2,3,0,1] row_mask:0xf bank_mask:0xf
	v_max_u32_dpp v27, v27, v27 quad_perm:[2,3,0,1] row_mask:0xf bank_mask:0xf
	v_max_u32_dpp v28, v28, v28 quad_perm:[2,3,0,1] row_mask:0xf bank_mask:0xf
	v_max_u32_dpp v29, v29, v29 quad_perm:[2,3,0,1] row_mask:0xf bank_mask:0xf
	v_max_u32_dpp v26, v26, v26 row_half_mirror row_mask:0xf bank_mask:0xf
	v_max_u32_dpp v27, v27, v27 row_half_mirror row_mask:0xf bank_mask:0xf
	v_max_u32_dpp v28, v28, v28 row_half_mirror row_mask:0xf bank_mask:0xf
	v_max_u32_dpp v29, v29, v29 row_half_mirror row_mask:0xf bank_mask:0xf
	v_max_u32_dpp v26, v26, v26 row_mirror row_mask:0xf bank_mask:0xf
	v_max_u32_dpp v27, v27, v27 row_mirror row_mask:0xf bank_mask:0xf
	v_max_u32_dpp v28, v28, v28 row_mirror row_mask:0xf bank_mask:0xf
	v_max_u32_dpp v29, v29, v29 row_mirror row_mask:0xf bank_mask:0xf
	v_max_u32_dpp v26, v26, v26 row_bcast:15 row_mask:0xa bank_mask:0xf
	v_max_u32_dpp v27, v27, v27 row_bcast:15 row_mask:0xa bank_mask:0xf
	v_max_u32_dpp v28, v28, v28 row_bcast:15 row_mask:0xa bank_mask:0xf
	v_max_u32_dpp v29, v29, v29 row_bcast:15 row_mask:0xa bank_mask:0xf
	v_max_u32_dpp v26, v26, v26 row_bcast:31 row_mask:0xc bank_mask:0xf
	v_max_u32_dpp v27, v27, v27 row_bcast:31 row_mask:0xc bank_mask:0xf
	v_max_u32_dpp v28, v28, v28 row_bcast:31 row_mask:0xc bank_mask:0xf
	v_max_u32_dpp v29, v29, v29 row_bcast:31 row_mask:0xc bank_mask:0xf
	v_readlane_b32 s14, v26, 63
	v_readlane_b32 s15, v27, 63
	v_readlane_b32 s34, v28, 63
	v_readlane_b32 s35, v29, 63
	v_writelane_b32 v82, s14, 11
	v_writelane_b32 v83, s15, 11
	v_writelane_b32 v84, s34, 11
	v_writelane_b32 v85, s35, 11
	v_cmp_ne_u32_e64 s[42:43], s14, v18
	v_cmp_ne_u32_e64 s[66:67], s14, v22
	v_cmp_ne_u32_e64 s[0:1], s15, v19
	v_cmp_ne_u32_e32 vcc, s15, v23
	v_cndmask_b32_e64 v18, 0, v18, s[42:43]
	v_cndmask_b32_e64 v22, 0, v22, s[66:67]
	v_cndmask_b32_e64 v19, 0, v19, s[0:1]
	v_cndmask_b32_e32 v23, 0, v23, vcc
	v_cmp_ne_u32_e64 s[42:43], s34, v20
	v_cmp_ne_u32_e64 s[66:67], s34, v24
	v_cmp_ne_u32_e64 s[0:1], s35, v21
	v_cmp_ne_u32_e32 vcc, s35, v25
	v_cndmask_b32_e64 v20, 0, v20, s[42:43]
	v_cndmask_b32_e64 v24, 0, v24, s[66:67]
	v_cndmask_b32_e64 v21, 0, v21, s[0:1]
	v_cndmask_b32_e32 v25, 0, v25, vcc
	v_max_u32_e32 v26, v18, v22
	v_max_u32_e32 v27, v19, v23
	v_max_u32_e32 v28, v20, v24
	v_max_u32_e32 v29, v21, v25
	v_max_u32_dpp v26, v26, v26 quad_perm:[1,0,3,2] row_mask:0xf bank_mask:0xf
	v_max_u32_dpp v27, v27, v27 quad_perm:[1,0,3,2] row_mask:0xf bank_mask:0xf
	v_max_u32_dpp v28, v28, v28 quad_perm:[1,0,3,2] row_mask:0xf bank_mask:0xf
	v_max_u32_dpp v29, v29, v29 quad_perm:[1,0,3,2] row_mask:0xf bank_mask:0xf
	v_max_u32_dpp v26, v26, v26 quad_perm:[2,3,0,1] row_mask:0xf bank_mask:0xf
	v_max_u32_dpp v27, v27, v27 quad_perm:[2,3,0,1] row_mask:0xf bank_mask:0xf
	v_max_u32_dpp v28, v28, v28 quad_perm:[2,3,0,1] row_mask:0xf bank_mask:0xf
	v_max_u32_dpp v29, v29, v29 quad_perm:[2,3,0,1] row_mask:0xf bank_mask:0xf
	v_max_u32_dpp v26, v26, v26 row_half_mirror row_mask:0xf bank_mask:0xf
	v_max_u32_dpp v27, v27, v27 row_half_mirror row_mask:0xf bank_mask:0xf
	v_max_u32_dpp v28, v28, v28 row_half_mirror row_mask:0xf bank_mask:0xf
	v_max_u32_dpp v29, v29, v29 row_half_mirror row_mask:0xf bank_mask:0xf
	v_max_u32_dpp v26, v26, v26 row_mirror row_mask:0xf bank_mask:0xf
	v_max_u32_dpp v27, v27, v27 row_mirror row_mask:0xf bank_mask:0xf
	v_max_u32_dpp v28, v28, v28 row_mirror row_mask:0xf bank_mask:0xf
	v_max_u32_dpp v29, v29, v29 row_mirror row_mask:0xf bank_mask:0xf
	v_max_u32_dpp v26, v26, v26 row_bcast:15 row_mask:0xa bank_mask:0xf
	v_max_u32_dpp v27, v27, v27 row_bcast:15 row_mask:0xa bank_mask:0xf
	v_max_u32_dpp v28, v28, v28 row_bcast:15 row_mask:0xa bank_mask:0xf
	v_max_u32_dpp v29, v29, v29 row_bcast:15 row_mask:0xa bank_mask:0xf
	v_max_u32_dpp v26, v26, v26 row_bcast:31 row_mask:0xc bank_mask:0xf
	v_max_u32_dpp v27, v27, v27 row_bcast:31 row_mask:0xc bank_mask:0xf
	v_max_u32_dpp v28, v28, v28 row_bcast:31 row_mask:0xc bank_mask:0xf
	v_max_u32_dpp v29, v29, v29 row_bcast:31 row_mask:0xc bank_mask:0xf
	v_readlane_b32 s14, v26, 63
	v_readlane_b32 s15, v27, 63
	v_readlane_b32 s34, v28, 63
	v_readlane_b32 s35, v29, 63
	v_writelane_b32 v82, s14, 12
	v_writelane_b32 v83, s15, 12
	v_writelane_b32 v84, s34, 12
	v_writelane_b32 v85, s35, 12
	v_and_b32_e32 v82, 127, v82
	v_sub_u32_e32 v82, 127, v82
	v_and_b32_e32 v83, 127, v83
	v_sub_u32_e32 v83, 127, v83
	v_and_b32_e32 v84, 127, v84
	v_sub_u32_e32 v84, 127, v84
	v_and_b32_e32 v85, 127, v85
	v_sub_u32_e32 v85, 127, v85
	s_add_i32 s19, s18, -1
	v_mov_b32_e32 v236, s19
	v_mov_b32_e32 v237, s18
	v_cmp_eq_u32_e64 s[14:15], 14, v184
	v_cmp_eq_u32_e64 s[34:35], 15, v184
	s_nop 0
	v_cndmask_b32_e64 v82, v82, v236, s[14:15]
	v_cndmask_b32_e64 v82, v82, v237, s[34:35]
	v_cndmask_b32_e64 v83, v83, v236, s[14:15]
	v_cndmask_b32_e64 v83, v83, v237, s[34:35]
	v_cndmask_b32_e64 v84, v84, v236, s[14:15]
	v_cndmask_b32_e64 v84, v84, v237, s[34:35]
	v_cndmask_b32_e64 v85, v85, v236, s[14:15]
	v_cndmask_b32_e64 v85, v85, v237, s[34:35]
	s_and_saveexec_b64 s[42:43], s[6:7]
	ds_write_b32 v196, v82 offset:51520
	ds_write_b32 v196, v83 offset:51584
	ds_write_b32 v196, v84 offset:51648
	ds_write_b32 v196, v85 offset:51712
	s_or_b64 exec, exec, s[42:43]
	s_branch .Ltopk_done_q1
